# sc8 + K-loop load stages: vmcnt(8) and lgkmcnt(0) waits merged into a single s_waitcnt before the pre-MFMA barrier
# speedup vs baseline: 1.0021x; 1.0021x over previous
.LBB0_256:
	v_add_u32_e32 v172, s70, v160
	v_add_u32_e32 v188, s71, v160
	ds_read_b128 v[154:157], v172
	ds_read_b128 v[164:167], v172 offset:1024
	ds_read_b128 v[168:171], v172 offset:2048
	ds_read_b128 v[172:175], v172 offset:3072
	ds_read_b128 v[176:179], v188
	ds_read_b128 v[180:183], v188 offset:1024
	ds_read_b128 v[184:187], v188 offset:2048
	ds_read_b128 v[188:191], v188 offset:3072
	s_add_i32 s75, s30, 2
	s_add_u32 s31, s28, 0xfffc0080
	s_addc_u32 s34, s29, -1
	s_cmp_eq_u32 s67, s30
	s_cselect_b32 s30, s26, s17
	s_cselect_b32 s35, s25, s34
	s_cselect_b32 s34, s24, s31
	s_cselect_b32 s31, s27, s19
	s_add_i32 m0, s58, 0xc000
	ds_read_b128 v[192:195], v163
	ds_read_b128 v[196:199], v163 offset:1024
	ds_read_b128 v[200:203], v163 offset:2048
	ds_read_b128 v[204:207], v163 offset:3072
	ds_read_b128 v[208:211], v163 offset:4096
	ds_read_b128 v[212:215], v163 offset:5120
	ds_read_b128 v[216:219], v163 offset:6144
	ds_read_b128 v[220:223], v163 offset:7168
	global_load_lds_dwordx4 v146, s[28:29]
	s_add_i32 m0, s58, 0xe000
	s_nop 0
	global_load_lds_dwordx4 v148, s[28:29]
	s_waitcnt vmcnt(8) lgkmcnt(0)
	s_barrier
	v_mfma_f32_16x16x32_bf16 v[42:45], v[154:157], v[192:195], v[42:45]
	v_mfma_f32_16x16x32_bf16 v[42:45], v[164:167], v[196:199], v[42:45]
	v_mfma_f32_16x16x32_bf16 v[54:57], v[164:167], v[204:207], v[54:57]
	v_mfma_f32_16x16x32_bf16 v[54:57], v[154:157], v[200:203], v[54:57]
	v_mfma_f32_16x16x32_bf16 v[66:69], v[154:157], v[208:211], v[66:69]
	v_mfma_f32_16x16x32_bf16 v[66:69], v[164:167], v[212:215], v[66:69]
	v_mfma_f32_16x16x32_bf16 v[62:65], v[164:167], v[220:223], v[62:65]
	v_mfma_f32_16x16x32_bf16 v[62:65], v[154:157], v[216:219], v[62:65]
	v_mfma_f32_16x16x32_bf16 v[46:49], v[168:171], v[216:219], v[46:49]
	v_mfma_f32_16x16x32_bf16 v[46:49], v[172:175], v[220:223], v[46:49]
	v_mfma_f32_16x16x32_bf16 v[50:53], v[172:175], v[212:215], v[50:53]
	v_mfma_f32_16x16x32_bf16 v[50:53], v[168:171], v[208:211], v[50:53]
	v_mfma_f32_16x16x32_bf16 v[38:41], v[168:171], v[200:203], v[38:41]
	v_mfma_f32_16x16x32_bf16 v[38:41], v[172:175], v[204:207], v[38:41]
	v_mfma_f32_16x16x32_bf16 v[26:29], v[172:175], v[196:199], v[26:29]
	v_mfma_f32_16x16x32_bf16 v[26:29], v[168:171], v[192:195], v[26:29]
	v_mfma_f32_16x16x32_bf16 v[14:17], v[176:179], v[192:195], v[14:17]
	v_mfma_f32_16x16x32_bf16 v[14:17], v[180:183], v[196:199], v[14:17]
	v_mfma_f32_16x16x32_bf16 v[22:25], v[180:183], v[204:207], v[22:25]
	v_mfma_f32_16x16x32_bf16 v[22:25], v[176:179], v[200:203], v[22:25]
	v_mfma_f32_16x16x32_bf16 v[30:33], v[176:179], v[208:211], v[30:33]
	v_mfma_f32_16x16x32_bf16 v[30:33], v[180:183], v[212:215], v[30:33]
	v_mfma_f32_16x16x32_bf16 v[34:37], v[180:183], v[220:223], v[34:37]
	v_mfma_f32_16x16x32_bf16 v[34:37], v[176:179], v[216:219], v[34:37]
	v_mfma_f32_16x16x32_bf16 v[18:21], v[184:187], v[216:219], v[18:21]
	v_mfma_f32_16x16x32_bf16 v[18:21], v[188:191], v[220:223], v[18:21]
	v_mfma_f32_16x16x32_bf16 v[10:13], v[188:191], v[212:215], v[10:13]
	v_mfma_f32_16x16x32_bf16 v[10:13], v[184:187], v[208:211], v[10:13]
	v_mfma_f32_16x16x32_bf16 v[6:9], v[184:187], v[200:203], v[6:9]
	v_mfma_f32_16x16x32_bf16 v[6:9], v[188:191], v[204:207], v[6:9]
	v_mfma_f32_16x16x32_bf16 v[2:5], v[188:191], v[196:199], v[2:5]
	v_mfma_f32_16x16x32_bf16 v[2:5], v[184:187], v[192:195], v[2:5]
	s_barrier
	s_add_i32 s50, s70, s54
	s_mov_b32 m0, s50
	ds_read_b128 v[192:195], v163 offset:16384
	ds_read_b128 v[196:199], v163 offset:17408
	ds_read_b128 v[200:203], v163 offset:18432
	ds_read_b128 v[204:207], v163 offset:19456
	ds_read_b128 v[208:211], v163 offset:20480
	ds_read_b128 v[212:215], v163 offset:21504
	ds_read_b128 v[216:219], v163 offset:22528
	ds_read_b128 v[220:223], v163 offset:23552
	global_load_lds_dwordx4 v134, s[30:31]
	s_add_i32 m0, s50, 0x2000
	s_add_u32 s76, s30, 0x40000
	v_lshl_add_u64 v[226:227], s[30:31], 0, v[130:131]
	s_addc_u32 s77, s31, 0
	s_add_i32 s50, s71, s54
	global_load_lds_dwordx4 v130, s[30:31]
	s_mov_b32 m0, s50
	v_lshl_add_u64 v[230:231], s[34:35], 0, v[132:133]
	global_load_lds_dwordx4 v134, s[76:77]
	s_add_i32 m0, s50, 0x2000
	s_nop 0
	global_load_lds_dwordx4 v130, s[76:77]
	v_lshl_add_u64 v[228:229], s[34:35], 0, v[136:137]
	s_mov_b32 m0, s58
	s_nop 0
	global_load_lds_dwordx4 v136, s[34:35]
	s_mov_b32 m0, s59
	s_nop 0
	global_load_lds_dwordx4 v132, s[34:35]
	s_waitcnt vmcnt(8) lgkmcnt(0)
	s_barrier
	v_mfma_f32_16x16x32_bf16 v[110:113], v[154:157], v[192:195], v[110:113]
	v_mfma_f32_16x16x32_bf16 v[110:113], v[164:167], v[196:199], v[110:113]
	v_mfma_f32_16x16x32_bf16 v[106:109], v[164:167], v[204:207], v[106:109]
	v_mfma_f32_16x16x32_bf16 v[106:109], v[154:157], v[200:203], v[106:109]
	v_mfma_f32_16x16x32_bf16 v[118:121], v[154:157], v[208:211], v[118:121]
	v_mfma_f32_16x16x32_bf16 v[118:121], v[164:167], v[212:215], v[118:121]
	v_mfma_f32_16x16x32_bf16 v[126:129], v[164:167], v[220:223], v[126:129]
	v_mfma_f32_16x16x32_bf16 v[126:129], v[154:157], v[216:219], v[126:129]
	v_mfma_f32_16x16x32_bf16 v[102:105], v[168:171], v[216:219], v[102:105]
	v_mfma_f32_16x16x32_bf16 v[102:105], v[172:175], v[220:223], v[102:105]
	v_mfma_f32_16x16x32_bf16 v[94:97], v[172:175], v[212:215], v[94:97]
	v_mfma_f32_16x16x32_bf16 v[94:97], v[168:171], v[208:211], v[94:97]
	v_mfma_f32_16x16x32_bf16 v[82:85], v[168:171], v[200:203], v[82:85]
	v_mfma_f32_16x16x32_bf16 v[82:85], v[172:175], v[204:207], v[82:85]
	v_mfma_f32_16x16x32_bf16 v[86:89], v[172:175], v[196:199], v[86:89]
	v_mfma_f32_16x16x32_bf16 v[86:89], v[168:171], v[192:195], v[86:89]
	v_mfma_f32_16x16x32_bf16 v[70:73], v[176:179], v[192:195], v[70:73]
	v_mfma_f32_16x16x32_bf16 v[70:73], v[180:183], v[196:199], v[70:73]
	v_mfma_f32_16x16x32_bf16 v[74:77], v[180:183], v[204:207], v[74:77]
	v_mfma_f32_16x16x32_bf16 v[74:77], v[176:179], v[200:203], v[74:77]
	v_mfma_f32_16x16x32_bf16 v[114:117], v[176:179], v[208:211], v[114:117]
	v_mfma_f32_16x16x32_bf16 v[114:117], v[180:183], v[212:215], v[114:117]
	v_mfma_f32_16x16x32_bf16 v[122:125], v[180:183], v[220:223], v[122:125]
	v_mfma_f32_16x16x32_bf16 v[122:125], v[176:179], v[216:219], v[122:125]
	v_mfma_f32_16x16x32_bf16 v[98:101], v[184:187], v[216:219], v[98:101]
	v_mfma_f32_16x16x32_bf16 v[98:101], v[188:191], v[220:223], v[98:101]
	v_mfma_f32_16x16x32_bf16 v[90:93], v[188:191], v[212:215], v[90:93]
	v_mfma_f32_16x16x32_bf16 v[90:93], v[184:187], v[208:211], v[90:93]
	v_mfma_f32_16x16x32_bf16 v[78:81], v[184:187], v[200:203], v[78:81]
	v_mfma_f32_16x16x32_bf16 v[78:81], v[188:191], v[204:207], v[78:81]
	v_mfma_f32_16x16x32_bf16 v[58:61], v[188:191], v[196:199], v[58:61]
	v_mfma_f32_16x16x32_bf16 v[58:61], v[184:187], v[192:195], v[58:61]
	s_barrier
	s_add_i32 s50, 0, 0x18000
	s_add_i32 s51, 0, 0x1c000
	v_add_u32_e32 v172, s50, v160
	v_add_u32_e32 v188, s51, v160
	ds_read_b128 v[154:157], v172
	ds_read_b128 v[164:167], v172 offset:1024
	ds_read_b128 v[168:171], v172 offset:2048
	ds_read_b128 v[172:175], v172 offset:3072
	ds_read_b128 v[176:179], v188
	ds_read_b128 v[180:183], v188 offset:1024
	ds_read_b128 v[184:187], v188 offset:2048
	ds_read_b128 v[188:191], v188 offset:3072
	s_add_u32 s34, s34, 0x40000
	s_addc_u32 s35, s35, 0
	s_mov_b32 m0, s60
	ds_read_b128 v[192:195], v163 offset:32768
	ds_read_b128 v[196:199], v163 offset:33792
	ds_read_b128 v[200:203], v163 offset:34816
	ds_read_b128 v[204:207], v163 offset:35840
	ds_read_b128 v[208:211], v163 offset:36864
	ds_read_b128 v[212:215], v163 offset:37888
	ds_read_b128 v[216:219], v163 offset:38912
	ds_read_b128 v[220:223], v163 offset:39936
	global_load_lds_dwordx4 v136, s[34:35]
	s_mov_b32 m0, s61
	s_nop 0
	global_load_lds_dwordx4 v132, s[34:35]
	s_waitcnt vmcnt(8) lgkmcnt(0)
	s_barrier
	v_mfma_f32_16x16x32_bf16 v[42:45], v[154:157], v[192:195], v[42:45]
	v_mfma_f32_16x16x32_bf16 v[42:45], v[164:167], v[196:199], v[42:45]
	v_mfma_f32_16x16x32_bf16 v[54:57], v[164:167], v[204:207], v[54:57]
	v_mfma_f32_16x16x32_bf16 v[54:57], v[154:157], v[200:203], v[54:57]
	v_mfma_f32_16x16x32_bf16 v[66:69], v[154:157], v[208:211], v[66:69]
	v_mfma_f32_16x16x32_bf16 v[66:69], v[164:167], v[212:215], v[66:69]
	v_mfma_f32_16x16x32_bf16 v[62:65], v[164:167], v[220:223], v[62:65]
	v_mfma_f32_16x16x32_bf16 v[62:65], v[154:157], v[216:219], v[62:65]
	v_mfma_f32_16x16x32_bf16 v[46:49], v[168:171], v[216:219], v[46:49]
	v_mfma_f32_16x16x32_bf16 v[46:49], v[172:175], v[220:223], v[46:49]
	v_mfma_f32_16x16x32_bf16 v[50:53], v[172:175], v[212:215], v[50:53]
	v_mfma_f32_16x16x32_bf16 v[50:53], v[168:171], v[208:211], v[50:53]
	v_mfma_f32_16x16x32_bf16 v[38:41], v[168:171], v[200:203], v[38:41]
	v_mfma_f32_16x16x32_bf16 v[38:41], v[172:175], v[204:207], v[38:41]
	v_mfma_f32_16x16x32_bf16 v[26:29], v[172:175], v[196:199], v[26:29]
	v_mfma_f32_16x16x32_bf16 v[26:29], v[168:171], v[192:195], v[26:29]
	v_mfma_f32_16x16x32_bf16 v[14:17], v[176:179], v[192:195], v[14:17]
	v_mfma_f32_16x16x32_bf16 v[14:17], v[180:183], v[196:199], v[14:17]
	v_mfma_f32_16x16x32_bf16 v[22:25], v[180:183], v[204:207], v[22:25]
	v_mfma_f32_16x16x32_bf16 v[22:25], v[176:179], v[200:203], v[22:25]
	v_mfma_f32_16x16x32_bf16 v[30:33], v[176:179], v[208:211], v[30:33]
	v_mfma_f32_16x16x32_bf16 v[30:33], v[180:183], v[212:215], v[30:33]
	v_mfma_f32_16x16x32_bf16 v[34:37], v[180:183], v[220:223], v[34:37]
	v_mfma_f32_16x16x32_bf16 v[34:37], v[176:179], v[216:219], v[34:37]
	v_mfma_f32_16x16x32_bf16 v[18:21], v[184:187], v[216:219], v[18:21]
	v_mfma_f32_16x16x32_bf16 v[18:21], v[188:191], v[220:223], v[18:21]
	v_mfma_f32_16x16x32_bf16 v[10:13], v[188:191], v[212:215], v[10:13]
	v_mfma_f32_16x16x32_bf16 v[10:13], v[184:187], v[208:211], v[10:13]
	v_mfma_f32_16x16x32_bf16 v[6:9], v[184:187], v[200:203], v[6:9]
	v_mfma_f32_16x16x32_bf16 v[6:9], v[188:191], v[204:207], v[6:9]
	v_mfma_f32_16x16x32_bf16 v[2:5], v[188:191], v[196:199], v[2:5]
	v_mfma_f32_16x16x32_bf16 v[2:5], v[184:187], v[192:195], v[2:5]
	s_barrier
	s_add_i32 s34, s50, s54
	s_mov_b32 m0, s34
	ds_read_b128 v[192:195], v163 offset:49152
	ds_read_b128 v[196:199], v163 offset:50176
	ds_read_b128 v[200:203], v163 offset:51200
	ds_read_b128 v[204:207], v163 offset:52224
	ds_read_b128 v[208:211], v163 offset:53248
	ds_read_b128 v[212:215], v163 offset:54272
	ds_read_b128 v[216:219], v163 offset:55296
	ds_read_b128 v[220:223], v163 offset:56320
	s_add_u32 s98, s30, s10
	s_addc_u32 s99, s31, s11
	global_load_lds_dwordx4 v134, s[98:99]
	s_add_i32 m0, s34, 0x2000
	s_add_u32 s30, s30, 0x40080
	v_lshl_add_u64 v[224:225], v[226:227], 0, s[10:11]
	s_addc_u32 s31, s31, 0
	s_add_i32 s34, s51, s54
	global_load_lds_dwordx4 v[224:225], off
	s_mov_b32 m0, s34
	s_nop 0
	global_load_lds_dwordx4 v134, s[30:31]
	s_add_i32 m0, s34, 0x2000
	s_nop 0
	global_load_lds_dwordx4 v130, s[30:31]
	v_lshl_add_u64 v[224:225], v[228:229], 0, s[10:11]
	s_mov_b32 m0, s65
	s_nop 0
	global_load_lds_dwordx4 v[224:225], off
	v_lshl_add_u64 v[224:225], v[230:231], 0, s[10:11]
	s_mov_b32 m0, s66
	s_nop 0
	global_load_lds_dwordx4 v[224:225], off
	s_waitcnt vmcnt(8) lgkmcnt(0)
	s_barrier
	v_mfma_f32_16x16x32_bf16 v[110:113], v[154:157], v[192:195], v[110:113]
	v_mfma_f32_16x16x32_bf16 v[110:113], v[164:167], v[196:199], v[110:113]
	v_mfma_f32_16x16x32_bf16 v[106:109], v[164:167], v[204:207], v[106:109]
	v_mfma_f32_16x16x32_bf16 v[106:109], v[154:157], v[200:203], v[106:109]
	v_mfma_f32_16x16x32_bf16 v[118:121], v[154:157], v[208:211], v[118:121]
	v_mfma_f32_16x16x32_bf16 v[118:121], v[164:167], v[212:215], v[118:121]
	v_mfma_f32_16x16x32_bf16 v[126:129], v[164:167], v[220:223], v[126:129]
	v_mfma_f32_16x16x32_bf16 v[126:129], v[154:157], v[216:219], v[126:129]
	v_mfma_f32_16x16x32_bf16 v[102:105], v[168:171], v[216:219], v[102:105]
	v_mfma_f32_16x16x32_bf16 v[102:105], v[172:175], v[220:223], v[102:105]
	v_mfma_f32_16x16x32_bf16 v[94:97], v[172:175], v[212:215], v[94:97]
	v_mfma_f32_16x16x32_bf16 v[94:97], v[168:171], v[208:211], v[94:97]
	v_mfma_f32_16x16x32_bf16 v[82:85], v[168:171], v[200:203], v[82:85]
	v_mfma_f32_16x16x32_bf16 v[82:85], v[172:175], v[204:207], v[82:85]
	v_mfma_f32_16x16x32_bf16 v[86:89], v[172:175], v[196:199], v[86:89]
	v_mfma_f32_16x16x32_bf16 v[86:89], v[168:171], v[192:195], v[86:89]
	v_mfma_f32_16x16x32_bf16 v[70:73], v[176:179], v[192:195], v[70:73]
	v_mfma_f32_16x16x32_bf16 v[70:73], v[180:183], v[196:199], v[70:73]
	v_mfma_f32_16x16x32_bf16 v[74:77], v[180:183], v[204:207], v[74:77]
	v_mfma_f32_16x16x32_bf16 v[74:77], v[176:179], v[200:203], v[74:77]
	v_mfma_f32_16x16x32_bf16 v[114:117], v[176:179], v[208:211], v[114:117]
	v_mfma_f32_16x16x32_bf16 v[114:117], v[180:183], v[212:215], v[114:117]
	v_mfma_f32_16x16x32_bf16 v[122:125], v[180:183], v[220:223], v[122:125]
	v_mfma_f32_16x16x32_bf16 v[122:125], v[176:179], v[216:219], v[122:125]
	v_mfma_f32_16x16x32_bf16 v[98:101], v[184:187], v[216:219], v[98:101]
	v_mfma_f32_16x16x32_bf16 v[98:101], v[188:191], v[220:223], v[98:101]
	v_mfma_f32_16x16x32_bf16 v[90:93], v[188:191], v[212:215], v[90:93]
	v_mfma_f32_16x16x32_bf16 v[90:93], v[184:187], v[208:211], v[90:93]
	v_mfma_f32_16x16x32_bf16 v[78:81], v[184:187], v[200:203], v[78:81]
	v_mfma_f32_16x16x32_bf16 v[78:81], v[188:191], v[204:207], v[78:81]
	v_mfma_f32_16x16x32_bf16 v[58:61], v[188:191], v[196:199], v[58:61]
	v_mfma_f32_16x16x32_bf16 v[58:61], v[184:187], v[192:195], v[58:61]
	s_barrier
	s_add_u32 s28, s28, 0x100
	s_addc_u32 s29, s29, 0
	s_add_u32 s17, s17, 0x100
	s_addc_u32 s19, s19, 0
	s_cmp_ge_i32 s75, s62
	s_mov_b32 s30, s75
	s_cbranch_scc0 .LBB0_256

.LBB0_351:
	v_add_u32_e32 v81, s62, v78
	s_waitcnt lgkmcnt(0)
	ds_read_b128 v[82:85], v81
	ds_read_b128 v[86:89], v81 offset:1024
	ds_read_b128 v[90:93], v81 offset:2048
	ds_read_b128 v[94:97], v81 offset:3072
	s_add_i32 s72, s24, 2
	s_add_u32 s22, s20, 0x100
	s_addc_u32 s23, s21, 0
	s_cmp_eq_u32 s61, s24
	s_cselect_b32 s24, s16, s70
	s_cselect_b32 s27, s15, s23
	s_cselect_b32 s26, s14, s22
	s_cselect_b32 s25, s17, s71
	s_mov_b32 m0, s63
	ds_read_b128 v[98:101], v79
	ds_read_b128 v[102:105], v79 offset:1024
	ds_read_b128 v[106:109], v79 offset:2048
	ds_read_b128 v[110:113], v79 offset:3072
	ds_read_b128 v[114:117], v79 offset:4096
	ds_read_b128 v[118:121], v79 offset:5120
	ds_read_b128 v[122:125], v79 offset:6144
	ds_read_b128 v[126:129], v79 offset:7168
	global_load_lds_dwordx4 v74, s[20:21]
	s_mov_b32 m0, s64
	s_nop 0
	global_load_lds_dwordx4 v76, s[20:21]
	s_waitcnt vmcnt(8) lgkmcnt(0)
	s_barrier
	v_mfma_f32_16x16x32_bf16 v[62:65], v[82:85], v[98:101], v[62:65]
	v_mfma_f32_16x16x32_bf16 v[62:65], v[86:89], v[102:105], v[62:65]
	v_mfma_f32_16x16x32_bf16 v[54:57], v[86:89], v[110:113], v[54:57]
	v_mfma_f32_16x16x32_bf16 v[54:57], v[82:85], v[106:109], v[54:57]
	v_mfma_f32_16x16x32_bf16 v[46:49], v[82:85], v[114:117], v[46:49]
	v_mfma_f32_16x16x32_bf16 v[46:49], v[86:89], v[118:121], v[46:49]
	v_mfma_f32_16x16x32_bf16 v[34:37], v[86:89], v[126:129], v[34:37]
	v_mfma_f32_16x16x32_bf16 v[34:37], v[82:85], v[122:125], v[34:37]
	v_mfma_f32_16x16x32_bf16 v[26:29], v[90:93], v[122:125], v[26:29]
	v_mfma_f32_16x16x32_bf16 v[26:29], v[94:97], v[126:129], v[26:29]
	v_mfma_f32_16x16x32_bf16 v[42:45], v[94:97], v[118:121], v[42:45]
	v_mfma_f32_16x16x32_bf16 v[42:45], v[90:93], v[114:117], v[42:45]
	v_mfma_f32_16x16x32_bf16 v[50:53], v[90:93], v[106:109], v[50:53]
	v_mfma_f32_16x16x32_bf16 v[50:53], v[94:97], v[110:113], v[50:53]
	v_mfma_f32_16x16x32_bf16 v[58:61], v[94:97], v[102:105], v[58:61]
	v_mfma_f32_16x16x32_bf16 v[58:61], v[90:93], v[98:101], v[58:61]
	s_barrier
	s_mov_b32 m0, s65
	s_add_u32 s20, s24, 0x10000
	ds_read_b128 v[98:101], v79 offset:16384
	ds_read_b128 v[102:105], v79 offset:17408
	ds_read_b128 v[106:109], v79 offset:18432
	ds_read_b128 v[110:113], v79 offset:19456
	ds_read_b128 v[114:117], v79 offset:20480
	ds_read_b128 v[118:121], v79 offset:21504
	ds_read_b128 v[122:125], v79 offset:22528
	ds_read_b128 v[126:129], v79 offset:23552
	global_load_lds_dwordx4 v70, s[24:25]
	s_mov_b32 m0, s66
	s_addc_u32 s21, s25, 0
	global_load_lds_dwordx4 v66, s[24:25]
	s_mov_b32 m0, s34
	global_load_lds_dwordx4 v70, s[20:21]
	s_mov_b32 m0, s35
	s_nop 0
	global_load_lds_dwordx4 v66, s[20:21]
	s_mov_b32 m0, s31
	s_nop 0
	global_load_lds_dwordx4 v72, s[26:27]
	s_mov_b32 m0, s52
	s_nop 0
	global_load_lds_dwordx4 v68, s[26:27]
	s_waitcnt vmcnt(8) lgkmcnt(0)
	s_barrier
	v_mfma_f32_16x16x32_bf16 v[38:41], v[82:85], v[98:101], v[38:41]
	v_mfma_f32_16x16x32_bf16 v[38:41], v[86:89], v[102:105], v[38:41]
	v_mfma_f32_16x16x32_bf16 v[22:25], v[86:89], v[110:113], v[22:25]
	v_mfma_f32_16x16x32_bf16 v[22:25], v[82:85], v[106:109], v[22:25]
	v_mfma_f32_16x16x32_bf16 v[14:17], v[82:85], v[114:117], v[14:17]
	v_mfma_f32_16x16x32_bf16 v[14:17], v[86:89], v[118:121], v[14:17]
	v_mfma_f32_16x16x32_bf16 v[6:9], v[86:89], v[126:129], v[6:9]
	v_mfma_f32_16x16x32_bf16 v[6:9], v[82:85], v[122:125], v[6:9]
	v_mfma_f32_16x16x32_bf16 v[2:5], v[90:93], v[122:125], v[2:5]
	v_mfma_f32_16x16x32_bf16 v[2:5], v[94:97], v[126:129], v[2:5]
	v_mfma_f32_16x16x32_bf16 v[10:13], v[94:97], v[118:121], v[10:13]
	v_mfma_f32_16x16x32_bf16 v[10:13], v[90:93], v[114:117], v[10:13]
	v_mfma_f32_16x16x32_bf16 v[18:21], v[90:93], v[106:109], v[18:21]
	v_mfma_f32_16x16x32_bf16 v[18:21], v[94:97], v[110:113], v[18:21]
	v_mfma_f32_16x16x32_bf16 v[30:33], v[94:97], v[102:105], v[30:33]
	v_mfma_f32_16x16x32_bf16 v[30:33], v[90:93], v[98:101], v[30:33]
	s_barrier
	v_add_u32_e32 v81, s67, v78
	ds_read_b128 v[82:85], v81
	ds_read_b128 v[86:89], v81 offset:1024
	ds_read_b128 v[90:93], v81 offset:2048
	ds_read_b128 v[94:97], v81 offset:3072
	s_add_u32 s20, s26, 0x18000
	s_addc_u32 s21, s27, 0
	s_mov_b32 m0, s53
	ds_read_b128 v[98:101], v79 offset:32768
	ds_read_b128 v[102:105], v79 offset:33792
	ds_read_b128 v[106:109], v79 offset:34816
	ds_read_b128 v[110:113], v79 offset:35840
	ds_read_b128 v[114:117], v79 offset:36864
	ds_read_b128 v[118:121], v79 offset:37888
	ds_read_b128 v[122:125], v79 offset:38912
	ds_read_b128 v[126:129], v79 offset:39936
	global_load_lds_dwordx4 v72, s[20:21]
	s_mov_b32 m0, s54
	s_nop 0
	global_load_lds_dwordx4 v68, s[20:21]
	s_waitcnt vmcnt(8) lgkmcnt(0)
	s_barrier
	v_mfma_f32_16x16x32_bf16 v[62:65], v[82:85], v[98:101], v[62:65]
	v_mfma_f32_16x16x32_bf16 v[62:65], v[86:89], v[102:105], v[62:65]
	v_mfma_f32_16x16x32_bf16 v[54:57], v[86:89], v[110:113], v[54:57]
	v_mfma_f32_16x16x32_bf16 v[54:57], v[82:85], v[106:109], v[54:57]
	v_mfma_f32_16x16x32_bf16 v[46:49], v[82:85], v[114:117], v[46:49]
	v_mfma_f32_16x16x32_bf16 v[46:49], v[86:89], v[118:121], v[46:49]
	v_mfma_f32_16x16x32_bf16 v[34:37], v[86:89], v[126:129], v[34:37]
	v_mfma_f32_16x16x32_bf16 v[34:37], v[82:85], v[122:125], v[34:37]
	v_mfma_f32_16x16x32_bf16 v[26:29], v[90:93], v[122:125], v[26:29]
	v_mfma_f32_16x16x32_bf16 v[26:29], v[94:97], v[126:129], v[26:29]
	v_mfma_f32_16x16x32_bf16 v[42:45], v[94:97], v[118:121], v[42:45]
	v_mfma_f32_16x16x32_bf16 v[42:45], v[90:93], v[114:117], v[42:45]
	v_mfma_f32_16x16x32_bf16 v[50:53], v[90:93], v[106:109], v[50:53]
	v_mfma_f32_16x16x32_bf16 v[50:53], v[94:97], v[110:113], v[50:53]
	v_mfma_f32_16x16x32_bf16 v[58:61], v[94:97], v[102:105], v[58:61]
	v_mfma_f32_16x16x32_bf16 v[58:61], v[90:93], v[98:101], v[58:61]
	s_barrier
	s_mov_b32 m0, s68
	s_add_u32 s20, s24, 0x10080
	ds_read_b128 v[98:101], v79 offset:49152
	ds_read_b128 v[102:105], v79 offset:50176
	ds_read_b128 v[106:109], v79 offset:51200
	ds_read_b128 v[110:113], v79 offset:52224
	ds_read_b128 v[114:117], v79 offset:53248
	ds_read_b128 v[118:121], v79 offset:54272
	ds_read_b128 v[122:125], v79 offset:55296
	ds_read_b128 v[126:129], v79 offset:56320
	s_add_u32 s98, s24, s6
	s_addc_u32 s99, s25, s7
	global_load_lds_dwordx4 v70, s[98:99]
	s_mov_b32 m0, s69
	s_addc_u32 s21, s25, 0
	s_add_u32 s100, s24, s6
	s_addc_u32 s101, s25, s7
	global_load_lds_dwordx4 v66, s[100:101]
	s_mov_b32 m0, s59
	s_nop 0
	global_load_lds_dwordx4 v70, s[20:21]
	s_mov_b32 m0, s60
	s_nop 0
	global_load_lds_dwordx4 v66, s[20:21]
	s_mov_b32 m0, s57
	s_nop 0
	s_add_u32 s98, s26, s6
	s_addc_u32 s99, s27, s7
	global_load_lds_dwordx4 v72, s[98:99]
	s_mov_b32 m0, s58
	s_nop 0
	s_add_u32 s100, s26, s6
	s_addc_u32 s101, s27, s7
	global_load_lds_dwordx4 v68, s[100:101]
	s_waitcnt vmcnt(8) lgkmcnt(0)
	s_barrier
	v_mfma_f32_16x16x32_bf16 v[38:41], v[82:85], v[98:101], v[38:41]
	v_mfma_f32_16x16x32_bf16 v[38:41], v[86:89], v[102:105], v[38:41]
	v_mfma_f32_16x16x32_bf16 v[22:25], v[86:89], v[110:113], v[22:25]
	v_mfma_f32_16x16x32_bf16 v[22:25], v[82:85], v[106:109], v[22:25]
	v_mfma_f32_16x16x32_bf16 v[14:17], v[82:85], v[114:117], v[14:17]
	v_mfma_f32_16x16x32_bf16 v[14:17], v[86:89], v[118:121], v[14:17]
	v_mfma_f32_16x16x32_bf16 v[6:9], v[86:89], v[126:129], v[6:9]
	v_mfma_f32_16x16x32_bf16 v[6:9], v[82:85], v[122:125], v[6:9]
	v_mfma_f32_16x16x32_bf16 v[2:5], v[90:93], v[122:125], v[2:5]
	v_mfma_f32_16x16x32_bf16 v[2:5], v[94:97], v[126:129], v[2:5]
	v_mfma_f32_16x16x32_bf16 v[10:13], v[94:97], v[118:121], v[10:13]
	v_mfma_f32_16x16x32_bf16 v[10:13], v[90:93], v[114:117], v[10:13]
	v_mfma_f32_16x16x32_bf16 v[18:21], v[90:93], v[106:109], v[18:21]
	v_mfma_f32_16x16x32_bf16 v[18:21], v[94:97], v[110:113], v[18:21]
	v_mfma_f32_16x16x32_bf16 v[30:33], v[94:97], v[102:105], v[30:33]
	v_mfma_f32_16x16x32_bf16 v[30:33], v[90:93], v[98:101], v[30:33]
	s_barrier
	s_add_u32 s70, s70, 0x100
	s_addc_u32 s71, s71, 0
	s_cmp_ge_i32 s72, s56
	s_mov_b64 s[20:21], s[22:23]
	s_mov_b32 s24, s72
	s_cbranch_scc0 .LBB0_351

.LBB0_468:
	v_add_u32_e32 v144, s62, v1
	ds_read_b128 v[150:153], v144
	ds_read_b128 v[154:157], v144 offset:1024
	ds_read_b128 v[158:161], v144 offset:2048
	ds_read_b128 v[162:165], v144 offset:3072
	v_add_u32_e32 v144, s63, v1
	ds_read_b128 v[166:169], v144
	ds_read_b128 v[170:173], v144 offset:1024
	ds_read_b128 v[174:177], v144 offset:2048
	ds_read_b128 v[178:181], v144 offset:3072
	s_add_i32 s77, s26, 2
	s_add_u32 s24, s22, 0x100
	s_addc_u32 s25, s23, 0
	s_cmp_eq_u32 s61, s26
	s_cselect_b32 s26, s16, s75
	s_cselect_b32 s29, s15, s25
	s_cselect_b32 s28, s14, s24
	s_cselect_b32 s27, s17, s76
	s_mov_b32 m0, s64
	ds_read_b128 v[182:185], v149
	ds_read_b128 v[186:189], v149 offset:1024
	ds_read_b128 v[190:193], v149 offset:2048
	ds_read_b128 v[194:197], v149 offset:3072
	ds_read_b128 v[198:201], v149 offset:4096
	ds_read_b128 v[202:205], v149 offset:5120
	ds_read_b128 v[206:209], v149 offset:6144
	ds_read_b128 v[210:213], v149 offset:7168
	global_load_lds_dwordx4 v140, s[22:23]
	s_mov_b32 m0, s65
	s_nop 0
	global_load_lds_dwordx4 v142, s[22:23]
	s_waitcnt vmcnt(8) lgkmcnt(0)
	s_barrier
	v_mfma_f32_16x16x32_bf16 v[126:129], v[150:153], v[182:185], v[126:129]
	v_mfma_f32_16x16x32_bf16 v[126:129], v[154:157], v[186:189], v[126:129]
	v_mfma_f32_16x16x32_bf16 v[110:113], v[154:157], v[194:197], v[110:113]
	v_mfma_f32_16x16x32_bf16 v[110:113], v[150:153], v[190:193], v[110:113]
	v_mfma_f32_16x16x32_bf16 v[94:97], v[150:153], v[198:201], v[94:97]
	v_mfma_f32_16x16x32_bf16 v[94:97], v[154:157], v[202:205], v[94:97]
	v_mfma_f32_16x16x32_bf16 v[78:81], v[154:157], v[210:213], v[78:81]
	v_mfma_f32_16x16x32_bf16 v[78:81], v[150:153], v[206:209], v[78:81]
	v_mfma_f32_16x16x32_bf16 v[74:77], v[158:161], v[206:209], v[74:77]
	v_mfma_f32_16x16x32_bf16 v[74:77], v[162:165], v[210:213], v[74:77]
	v_mfma_f32_16x16x32_bf16 v[90:93], v[162:165], v[202:205], v[90:93]
	v_mfma_f32_16x16x32_bf16 v[90:93], v[158:161], v[198:201], v[90:93]
	v_mfma_f32_16x16x32_bf16 v[106:109], v[158:161], v[190:193], v[106:109]
	v_mfma_f32_16x16x32_bf16 v[106:109], v[162:165], v[194:197], v[106:109]
	v_mfma_f32_16x16x32_bf16 v[122:125], v[162:165], v[186:189], v[122:125]
	v_mfma_f32_16x16x32_bf16 v[122:125], v[158:161], v[182:185], v[122:125]
	v_mfma_f32_16x16x32_bf16 v[118:121], v[166:169], v[182:185], v[118:121]
	v_mfma_f32_16x16x32_bf16 v[118:121], v[170:173], v[186:189], v[118:121]
	v_mfma_f32_16x16x32_bf16 v[102:105], v[170:173], v[194:197], v[102:105]
	v_mfma_f32_16x16x32_bf16 v[102:105], v[166:169], v[190:193], v[102:105]
	v_mfma_f32_16x16x32_bf16 v[86:89], v[166:169], v[198:201], v[86:89]
	v_mfma_f32_16x16x32_bf16 v[86:89], v[170:173], v[202:205], v[86:89]
	v_mfma_f32_16x16x32_bf16 v[70:73], v[170:173], v[210:213], v[70:73]
	v_mfma_f32_16x16x32_bf16 v[70:73], v[166:169], v[206:209], v[70:73]
	v_mfma_f32_16x16x32_bf16 v[66:69], v[174:177], v[206:209], v[66:69]
	v_mfma_f32_16x16x32_bf16 v[66:69], v[178:181], v[210:213], v[66:69]
	v_mfma_f32_16x16x32_bf16 v[82:85], v[178:181], v[202:205], v[82:85]
	v_mfma_f32_16x16x32_bf16 v[82:85], v[174:177], v[198:201], v[82:85]
	v_mfma_f32_16x16x32_bf16 v[98:101], v[174:177], v[190:193], v[98:101]
	v_mfma_f32_16x16x32_bf16 v[98:101], v[178:181], v[194:197], v[98:101]
	v_mfma_f32_16x16x32_bf16 v[114:117], v[178:181], v[186:189], v[114:117]
	v_mfma_f32_16x16x32_bf16 v[114:117], v[174:177], v[182:185], v[114:117]
	s_barrier
	s_mov_b32 m0, s66
	s_add_u32 s22, s26, 0x18000
	ds_read_b128 v[182:185], v149 offset:16384
	ds_read_b128 v[186:189], v149 offset:17408
	ds_read_b128 v[190:193], v149 offset:18432
	ds_read_b128 v[194:197], v149 offset:19456
	ds_read_b128 v[198:201], v149 offset:20480
	ds_read_b128 v[202:205], v149 offset:21504
	ds_read_b128 v[206:209], v149 offset:22528
	ds_read_b128 v[210:213], v149 offset:23552
	global_load_lds_dwordx4 v134, s[26:27]
	v_lshl_add_u64 v[214:215], s[26:27], 0, v[130:131]
	s_mov_b32 m0, s67
	s_addc_u32 s23, s27, 0
	global_load_lds_dwordx4 v130, s[26:27]
	s_mov_b32 m0, s68
	global_load_lds_dwordx4 v134, s[22:23]
	s_mov_b32 m0, s69
	s_nop 0
	global_load_lds_dwordx4 v130, s[22:23]
	s_mov_b32 m0, s34
	s_nop 0
	global_load_lds_dwordx4 v136, s[28:29]
	s_mov_b32 m0, s35
	s_nop 0
	global_load_lds_dwordx4 v132, s[28:29]
	s_waitcnt vmcnt(8) lgkmcnt(0)
	s_barrier
	v_mfma_f32_16x16x32_bf16 v[62:65], v[150:153], v[182:185], v[62:65]
	v_mfma_f32_16x16x32_bf16 v[62:65], v[154:157], v[186:189], v[62:65]
	v_mfma_f32_16x16x32_bf16 v[46:49], v[154:157], v[194:197], v[46:49]
	v_mfma_f32_16x16x32_bf16 v[46:49], v[150:153], v[190:193], v[46:49]
	v_mfma_f32_16x16x32_bf16 v[30:33], v[150:153], v[198:201], v[30:33]
	v_mfma_f32_16x16x32_bf16 v[30:33], v[154:157], v[202:205], v[30:33]
	v_mfma_f32_16x16x32_bf16 v[14:17], v[154:157], v[210:213], v[14:17]
	v_mfma_f32_16x16x32_bf16 v[14:17], v[150:153], v[206:209], v[14:17]
	v_mfma_f32_16x16x32_bf16 v[10:13], v[158:161], v[206:209], v[10:13]
	v_mfma_f32_16x16x32_bf16 v[10:13], v[162:165], v[210:213], v[10:13]
	v_mfma_f32_16x16x32_bf16 v[26:29], v[162:165], v[202:205], v[26:29]
	v_mfma_f32_16x16x32_bf16 v[26:29], v[158:161], v[198:201], v[26:29]
	v_mfma_f32_16x16x32_bf16 v[42:45], v[158:161], v[190:193], v[42:45]
	v_mfma_f32_16x16x32_bf16 v[42:45], v[162:165], v[194:197], v[42:45]
	v_mfma_f32_16x16x32_bf16 v[58:61], v[162:165], v[186:189], v[58:61]
	v_mfma_f32_16x16x32_bf16 v[58:61], v[158:161], v[182:185], v[58:61]
	v_mfma_f32_16x16x32_bf16 v[54:57], v[166:169], v[182:185], v[54:57]
	v_mfma_f32_16x16x32_bf16 v[54:57], v[170:173], v[186:189], v[54:57]
	v_mfma_f32_16x16x32_bf16 v[38:41], v[170:173], v[194:197], v[38:41]
	v_mfma_f32_16x16x32_bf16 v[38:41], v[166:169], v[190:193], v[38:41]
	v_mfma_f32_16x16x32_bf16 v[22:25], v[166:169], v[198:201], v[22:25]
	v_mfma_f32_16x16x32_bf16 v[22:25], v[170:173], v[202:205], v[22:25]
	v_mfma_f32_16x16x32_bf16 v[6:9], v[170:173], v[210:213], v[6:9]
	v_mfma_f32_16x16x32_bf16 v[6:9], v[166:169], v[206:209], v[6:9]
	v_mfma_f32_16x16x32_bf16 v[2:5], v[174:177], v[206:209], v[2:5]
	v_mfma_f32_16x16x32_bf16 v[2:5], v[178:181], v[210:213], v[2:5]
	v_mfma_f32_16x16x32_bf16 v[18:21], v[178:181], v[202:205], v[18:21]
	v_mfma_f32_16x16x32_bf16 v[18:21], v[174:177], v[198:201], v[18:21]
	v_mfma_f32_16x16x32_bf16 v[34:37], v[174:177], v[190:193], v[34:37]
	v_mfma_f32_16x16x32_bf16 v[34:37], v[178:181], v[194:197], v[34:37]
	v_mfma_f32_16x16x32_bf16 v[50:53], v[178:181], v[186:189], v[50:53]
	v_mfma_f32_16x16x32_bf16 v[50:53], v[174:177], v[182:185], v[50:53]
	s_barrier
	v_add_u32_e32 v162, s70, v1
	v_add_u32_e32 v178, s71, v1
	ds_read_b128 v[150:153], v162
	ds_read_b128 v[154:157], v162 offset:1024
	ds_read_b128 v[158:161], v162 offset:2048
	ds_read_b128 v[162:165], v162 offset:3072
	ds_read_b128 v[166:169], v178
	ds_read_b128 v[170:173], v178 offset:1024
	ds_read_b128 v[174:177], v178 offset:2048
	ds_read_b128 v[178:181], v178 offset:3072
	s_add_u32 s22, s28, 0x18000
	s_addc_u32 s23, s29, 0
	s_mov_b32 m0, s52
	ds_read_b128 v[182:185], v149 offset:32768
	ds_read_b128 v[186:189], v149 offset:33792
	ds_read_b128 v[190:193], v149 offset:34816
	ds_read_b128 v[194:197], v149 offset:35840
	ds_read_b128 v[198:201], v149 offset:36864
	ds_read_b128 v[202:205], v149 offset:37888
	ds_read_b128 v[206:209], v149 offset:38912
	ds_read_b128 v[210:213], v149 offset:39936
	global_load_lds_dwordx4 v136, s[22:23]
	s_mov_b32 m0, s53
	s_nop 0
	global_load_lds_dwordx4 v132, s[22:23]
	s_waitcnt vmcnt(8) lgkmcnt(0)
	s_barrier
	v_mfma_f32_16x16x32_bf16 v[126:129], v[150:153], v[182:185], v[126:129]
	v_mfma_f32_16x16x32_bf16 v[126:129], v[154:157], v[186:189], v[126:129]
	v_mfma_f32_16x16x32_bf16 v[110:113], v[154:157], v[194:197], v[110:113]
	v_mfma_f32_16x16x32_bf16 v[110:113], v[150:153], v[190:193], v[110:113]
	v_mfma_f32_16x16x32_bf16 v[94:97], v[150:153], v[198:201], v[94:97]
	v_mfma_f32_16x16x32_bf16 v[94:97], v[154:157], v[202:205], v[94:97]
	v_mfma_f32_16x16x32_bf16 v[78:81], v[154:157], v[210:213], v[78:81]
	v_mfma_f32_16x16x32_bf16 v[78:81], v[150:153], v[206:209], v[78:81]
	v_mfma_f32_16x16x32_bf16 v[74:77], v[158:161], v[206:209], v[74:77]
	v_mfma_f32_16x16x32_bf16 v[74:77], v[162:165], v[210:213], v[74:77]
	v_mfma_f32_16x16x32_bf16 v[90:93], v[162:165], v[202:205], v[90:93]
	v_mfma_f32_16x16x32_bf16 v[90:93], v[158:161], v[198:201], v[90:93]
	v_mfma_f32_16x16x32_bf16 v[106:109], v[158:161], v[190:193], v[106:109]
	v_mfma_f32_16x16x32_bf16 v[106:109], v[162:165], v[194:197], v[106:109]
	v_mfma_f32_16x16x32_bf16 v[122:125], v[162:165], v[186:189], v[122:125]
	v_mfma_f32_16x16x32_bf16 v[122:125], v[158:161], v[182:185], v[122:125]
	v_mfma_f32_16x16x32_bf16 v[118:121], v[166:169], v[182:185], v[118:121]
	v_mfma_f32_16x16x32_bf16 v[118:121], v[170:173], v[186:189], v[118:121]
	v_mfma_f32_16x16x32_bf16 v[102:105], v[170:173], v[194:197], v[102:105]
	v_mfma_f32_16x16x32_bf16 v[102:105], v[166:169], v[190:193], v[102:105]
	v_mfma_f32_16x16x32_bf16 v[86:89], v[166:169], v[198:201], v[86:89]
	v_mfma_f32_16x16x32_bf16 v[86:89], v[170:173], v[202:205], v[86:89]
	v_mfma_f32_16x16x32_bf16 v[70:73], v[170:173], v[210:213], v[70:73]
	v_mfma_f32_16x16x32_bf16 v[70:73], v[166:169], v[206:209], v[70:73]
	v_mfma_f32_16x16x32_bf16 v[66:69], v[174:177], v[206:209], v[66:69]
	v_mfma_f32_16x16x32_bf16 v[66:69], v[178:181], v[210:213], v[66:69]
	v_mfma_f32_16x16x32_bf16 v[82:85], v[178:181], v[202:205], v[82:85]
	v_mfma_f32_16x16x32_bf16 v[82:85], v[174:177], v[198:201], v[82:85]
	v_mfma_f32_16x16x32_bf16 v[98:101], v[174:177], v[190:193], v[98:101]
	v_mfma_f32_16x16x32_bf16 v[98:101], v[178:181], v[194:197], v[98:101]
	v_mfma_f32_16x16x32_bf16 v[114:117], v[178:181], v[186:189], v[114:117]
	v_mfma_f32_16x16x32_bf16 v[114:117], v[174:177], v[182:185], v[114:117]
	s_barrier
	s_mov_b32 m0, s72
	ds_read_b128 v[182:185], v149 offset:49152
	ds_read_b128 v[186:189], v149 offset:50176
	ds_read_b128 v[190:193], v149 offset:51200
	ds_read_b128 v[194:197], v149 offset:52224
	ds_read_b128 v[198:201], v149 offset:53248
	ds_read_b128 v[202:205], v149 offset:54272
	ds_read_b128 v[206:209], v149 offset:55296
	ds_read_b128 v[210:213], v149 offset:56320
	s_add_u32 s98, s26, s4
	s_addc_u32 s99, s27, s5
	global_load_lds_dwordx4 v134, s[98:99]
	s_add_i32 m0, s72, 0x2000
	s_add_u32 s22, s26, 0x18080
	v_lshl_add_u64 v[144:145], v[214:215], 0, s[4:5]
	s_addc_u32 s23, s27, 0
	s_add_i32 s26, s71, s30
	global_load_lds_dwordx4 v[144:145], off
	s_mov_b32 m0, s26
	s_nop 0
	global_load_lds_dwordx4 v134, s[22:23]
	s_add_i32 m0, s26, 0x2000
	s_nop 0
	global_load_lds_dwordx4 v130, s[22:23]
	s_mov_b32 m0, s59
	s_nop 0
	s_add_u32 s100, s28, s4
	s_addc_u32 s101, s29, s5
	global_load_lds_dwordx4 v136, s[100:101]
	s_mov_b32 m0, s60
	s_nop 0
	s_add_u32 s98, s28, s4
	s_addc_u32 s99, s29, s5
	global_load_lds_dwordx4 v132, s[98:99]
	s_waitcnt vmcnt(8) lgkmcnt(0)
	s_barrier
	v_mfma_f32_16x16x32_bf16 v[62:65], v[150:153], v[182:185], v[62:65]
	v_mfma_f32_16x16x32_bf16 v[62:65], v[154:157], v[186:189], v[62:65]
	v_mfma_f32_16x16x32_bf16 v[46:49], v[154:157], v[194:197], v[46:49]
	v_mfma_f32_16x16x32_bf16 v[46:49], v[150:153], v[190:193], v[46:49]
	v_mfma_f32_16x16x32_bf16 v[30:33], v[150:153], v[198:201], v[30:33]
	v_mfma_f32_16x16x32_bf16 v[30:33], v[154:157], v[202:205], v[30:33]
	v_mfma_f32_16x16x32_bf16 v[14:17], v[154:157], v[210:213], v[14:17]
	v_mfma_f32_16x16x32_bf16 v[14:17], v[150:153], v[206:209], v[14:17]
	v_mfma_f32_16x16x32_bf16 v[10:13], v[158:161], v[206:209], v[10:13]
	v_mfma_f32_16x16x32_bf16 v[10:13], v[162:165], v[210:213], v[10:13]
	v_mfma_f32_16x16x32_bf16 v[26:29], v[162:165], v[202:205], v[26:29]
	v_mfma_f32_16x16x32_bf16 v[26:29], v[158:161], v[198:201], v[26:29]
	v_mfma_f32_16x16x32_bf16 v[42:45], v[158:161], v[190:193], v[42:45]
	v_mfma_f32_16x16x32_bf16 v[42:45], v[162:165], v[194:197], v[42:45]
	v_mfma_f32_16x16x32_bf16 v[58:61], v[162:165], v[186:189], v[58:61]
	v_mfma_f32_16x16x32_bf16 v[58:61], v[158:161], v[182:185], v[58:61]
	v_mfma_f32_16x16x32_bf16 v[54:57], v[166:169], v[182:185], v[54:57]
	v_mfma_f32_16x16x32_bf16 v[54:57], v[170:173], v[186:189], v[54:57]
	v_mfma_f32_16x16x32_bf16 v[38:41], v[170:173], v[194:197], v[38:41]
	v_mfma_f32_16x16x32_bf16 v[38:41], v[166:169], v[190:193], v[38:41]
	v_mfma_f32_16x16x32_bf16 v[22:25], v[166:169], v[198:201], v[22:25]
	v_mfma_f32_16x16x32_bf16 v[22:25], v[170:173], v[202:205], v[22:25]
	v_mfma_f32_16x16x32_bf16 v[6:9], v[170:173], v[210:213], v[6:9]
	v_mfma_f32_16x16x32_bf16 v[6:9], v[166:169], v[206:209], v[6:9]
	v_mfma_f32_16x16x32_bf16 v[2:5], v[174:177], v[206:209], v[2:5]
	v_mfma_f32_16x16x32_bf16 v[2:5], v[178:181], v[210:213], v[2:5]
	v_mfma_f32_16x16x32_bf16 v[18:21], v[178:181], v[202:205], v[18:21]
	v_mfma_f32_16x16x32_bf16 v[18:21], v[174:177], v[198:201], v[18:21]
	v_mfma_f32_16x16x32_bf16 v[34:37], v[174:177], v[190:193], v[34:37]
	v_mfma_f32_16x16x32_bf16 v[34:37], v[178:181], v[194:197], v[34:37]
	v_mfma_f32_16x16x32_bf16 v[50:53], v[178:181], v[186:189], v[50:53]
	v_mfma_f32_16x16x32_bf16 v[50:53], v[174:177], v[182:185], v[50:53]
	s_barrier
	s_add_u32 s75, s75, 0x100
	s_addc_u32 s76, s76, 0
	s_cmp_ge_i32 s77, s57
	s_mov_b64 s[22:23], s[24:25]
	s_mov_b32 s26, s77
	s_cbranch_scc0 .LBB0_468

.LBB0_599:
	v_add_u32_e32 v142, s74, v199
	v_add_u32_e32 v162, s75, v199
	ds_read_b128 v[130:133], v142
	ds_read_b128 v[134:137], v142 offset:1024
	ds_read_b128 v[138:141], v142 offset:2048
	ds_read_b128 v[142:145], v142 offset:3072
	ds_read_b128 v[146:149], v162
	ds_read_b128 v[150:153], v162 offset:1024
	ds_read_b128 v[174:177], v162 offset:2048
	ds_read_b128 v[178:181], v162 offset:3072
	s_add_i32 s31, s52, 2
	s_add_u32 s50, s34, 0x3ff000
	s_addc_u32 s51, s35, 0
	s_cmp_eq_u32 s71, s52
	s_cselect_b32 s56, s26, s50
	s_cselect_b32 s57, s27, s51
	s_cselect_b32 s54, s28, s23
	s_cselect_b32 s55, s29, s25
	s_add_u32 s52, s56, 0x400000
	s_addc_u32 s53, s57, 0
	s_add_i32 m0, s59, 0xc000
	ds_read_b128 v[182:185], v200
	ds_read_b128 v[186:189], v200 offset:1024
	ds_read_b128 v[190:193], v200 offset:2048
	ds_read_b128 v[194:197], v200 offset:3072
	ds_read_b128 v[202:205], v200 offset:4096
	ds_read_b128 v[206:209], v200 offset:5120
	ds_read_b128 v[210:213], v200 offset:6144
	ds_read_b128 v[214:217], v200 offset:7168
	global_load_lds_dwordx4 v164, s[34:35]
	s_add_i32 m0, s59, 0xe000
	s_nop 0
	global_load_lds_dwordx4 v166, s[34:35]
	s_waitcnt vmcnt(8) lgkmcnt(0)
	s_barrier
	v_mfma_f32_16x16x32_bf16 v[118:121], v[130:133], v[182:185], v[118:121]
	v_mfma_f32_16x16x32_bf16 v[118:121], v[134:137], v[186:189], v[118:121]
	v_mfma_f32_16x16x32_bf16 v[110:113], v[134:137], v[194:197], v[110:113]
	v_mfma_f32_16x16x32_bf16 v[110:113], v[130:133], v[190:193], v[110:113]
	v_mfma_f32_16x16x32_bf16 v[94:97], v[130:133], v[202:205], v[94:97]
	v_mfma_f32_16x16x32_bf16 v[94:97], v[134:137], v[206:209], v[94:97]
	v_mfma_f32_16x16x32_bf16 v[78:81], v[134:137], v[214:217], v[78:81]
	v_mfma_f32_16x16x32_bf16 v[78:81], v[130:133], v[210:213], v[78:81]
	v_mfma_f32_16x16x32_bf16 v[74:77], v[138:141], v[210:213], v[74:77]
	v_mfma_f32_16x16x32_bf16 v[74:77], v[142:145], v[214:217], v[74:77]
	v_mfma_f32_16x16x32_bf16 v[90:93], v[142:145], v[206:209], v[90:93]
	v_mfma_f32_16x16x32_bf16 v[90:93], v[138:141], v[202:205], v[90:93]
	v_mfma_f32_16x16x32_bf16 v[106:109], v[138:141], v[190:193], v[106:109]
	v_mfma_f32_16x16x32_bf16 v[106:109], v[142:145], v[194:197], v[106:109]
	v_mfma_f32_16x16x32_bf16 v[122:125], v[142:145], v[186:189], v[122:125]
	v_mfma_f32_16x16x32_bf16 v[122:125], v[138:141], v[182:185], v[122:125]
	v_mfma_f32_16x16x32_bf16 v[126:129], v[146:149], v[182:185], v[126:129]
	v_mfma_f32_16x16x32_bf16 v[126:129], v[150:153], v[186:189], v[126:129]
	v_mfma_f32_16x16x32_bf16 v[102:105], v[150:153], v[194:197], v[102:105]
	v_mfma_f32_16x16x32_bf16 v[102:105], v[146:149], v[190:193], v[102:105]
	v_mfma_f32_16x16x32_bf16 v[86:89], v[146:149], v[202:205], v[86:89]
	v_mfma_f32_16x16x32_bf16 v[86:89], v[150:153], v[206:209], v[86:89]
	v_mfma_f32_16x16x32_bf16 v[70:73], v[150:153], v[214:217], v[70:73]
	v_mfma_f32_16x16x32_bf16 v[70:73], v[146:149], v[210:213], v[70:73]
	v_mfma_f32_16x16x32_bf16 v[66:69], v[174:177], v[210:213], v[66:69]
	v_mfma_f32_16x16x32_bf16 v[66:69], v[178:181], v[214:217], v[66:69]
	v_mfma_f32_16x16x32_bf16 v[82:85], v[178:181], v[206:209], v[82:85]
	v_mfma_f32_16x16x32_bf16 v[82:85], v[174:177], v[202:205], v[82:85]
	v_mfma_f32_16x16x32_bf16 v[98:101], v[174:177], v[190:193], v[98:101]
	v_mfma_f32_16x16x32_bf16 v[98:101], v[178:181], v[194:197], v[98:101]
	v_mfma_f32_16x16x32_bf16 v[114:117], v[178:181], v[186:189], v[114:117]
	v_mfma_f32_16x16x32_bf16 v[114:117], v[174:177], v[182:185], v[114:117]
	s_barrier
	s_add_i32 s50, s74, s41
	s_mov_b32 m0, s50
	ds_read_b128 v[182:185], v200 offset:16384
	ds_read_b128 v[186:189], v200 offset:17408
	ds_read_b128 v[190:193], v200 offset:18432
	ds_read_b128 v[194:197], v200 offset:19456
	ds_read_b128 v[202:205], v200 offset:20480
	ds_read_b128 v[206:209], v200 offset:21504
	ds_read_b128 v[210:213], v200 offset:22528
	ds_read_b128 v[214:217], v200 offset:23552
	global_load_lds_dwordx4 v156, s[54:55]
	s_add_i32 m0, s50, 0x2000
	s_add_u32 s50, s54, 0x20000
	v_lshl_add_u64 v[220:221], s[54:55], 0, v[160:161]
	s_addc_u32 s51, s55, 0
	s_add_i32 s78, s75, s41
	global_load_lds_dwordx4 v160, s[54:55]
	s_mov_b32 m0, s78
	s_nop 0
	global_load_lds_dwordx4 v156, s[50:51]
	s_add_i32 m0, s78, 0x2000
	s_nop 0
	global_load_lds_dwordx4 v160, s[50:51]
	s_mov_b32 m0, s59
	s_nop 0
	global_load_lds_dwordx4 v154, s[56:57]
	s_mov_b32 m0, s60
	s_nop 0
	global_load_lds_dwordx4 v158, s[56:57]
	s_waitcnt vmcnt(8) lgkmcnt(0)
	s_barrier
	v_mfma_f32_16x16x32_bf16 v[62:65], v[130:133], v[182:185], v[62:65]
	v_mfma_f32_16x16x32_bf16 v[62:65], v[134:137], v[186:189], v[62:65]
	v_mfma_f32_16x16x32_bf16 v[46:49], v[134:137], v[194:197], v[46:49]
	v_mfma_f32_16x16x32_bf16 v[46:49], v[130:133], v[190:193], v[46:49]
	v_mfma_f32_16x16x32_bf16 v[30:33], v[130:133], v[202:205], v[30:33]
	v_mfma_f32_16x16x32_bf16 v[30:33], v[134:137], v[206:209], v[30:33]
	v_mfma_f32_16x16x32_bf16 v[14:17], v[134:137], v[214:217], v[14:17]
	v_mfma_f32_16x16x32_bf16 v[14:17], v[130:133], v[210:213], v[14:17]
	v_mfma_f32_16x16x32_bf16 v[10:13], v[138:141], v[210:213], v[10:13]
	v_mfma_f32_16x16x32_bf16 v[10:13], v[142:145], v[214:217], v[10:13]
	v_mfma_f32_16x16x32_bf16 v[26:29], v[142:145], v[206:209], v[26:29]
	v_mfma_f32_16x16x32_bf16 v[26:29], v[138:141], v[202:205], v[26:29]
	v_mfma_f32_16x16x32_bf16 v[42:45], v[138:141], v[190:193], v[42:45]
	v_mfma_f32_16x16x32_bf16 v[42:45], v[142:145], v[194:197], v[42:45]
	v_mfma_f32_16x16x32_bf16 v[58:61], v[142:145], v[186:189], v[58:61]
	v_mfma_f32_16x16x32_bf16 v[58:61], v[138:141], v[182:185], v[58:61]
	v_mfma_f32_16x16x32_bf16 v[54:57], v[146:149], v[182:185], v[54:57]
	v_mfma_f32_16x16x32_bf16 v[54:57], v[150:153], v[186:189], v[54:57]
	v_mfma_f32_16x16x32_bf16 v[38:41], v[150:153], v[194:197], v[38:41]
	v_mfma_f32_16x16x32_bf16 v[38:41], v[146:149], v[190:193], v[38:41]
	v_mfma_f32_16x16x32_bf16 v[22:25], v[146:149], v[202:205], v[22:25]
	v_mfma_f32_16x16x32_bf16 v[22:25], v[150:153], v[206:209], v[22:25]
	v_mfma_f32_16x16x32_bf16 v[6:9], v[150:153], v[214:217], v[6:9]
	v_mfma_f32_16x16x32_bf16 v[6:9], v[146:149], v[210:213], v[6:9]
	v_mfma_f32_16x16x32_bf16 v[2:5], v[174:177], v[210:213], v[2:5]
	v_mfma_f32_16x16x32_bf16 v[2:5], v[178:181], v[214:217], v[2:5]
	v_mfma_f32_16x16x32_bf16 v[18:21], v[178:181], v[206:209], v[18:21]
	v_mfma_f32_16x16x32_bf16 v[18:21], v[174:177], v[202:205], v[18:21]
	v_mfma_f32_16x16x32_bf16 v[34:37], v[174:177], v[190:193], v[34:37]
	v_mfma_f32_16x16x32_bf16 v[34:37], v[178:181], v[194:197], v[34:37]
	v_mfma_f32_16x16x32_bf16 v[50:53], v[178:181], v[186:189], v[50:53]
	v_mfma_f32_16x16x32_bf16 v[50:53], v[174:177], v[182:185], v[50:53]
	s_barrier
	s_add_i32 s78, 0, 0x18000
	s_add_i32 s79, 0, 0x1c000
	v_add_u32_e32 v142, s78, v199
	v_add_u32_e32 v162, s79, v199
	ds_read_b128 v[130:133], v142
	ds_read_b128 v[134:137], v142 offset:1024
	ds_read_b128 v[138:141], v142 offset:2048
	ds_read_b128 v[142:145], v142 offset:3072
	ds_read_b128 v[146:149], v162
	ds_read_b128 v[150:153], v162 offset:1024
	ds_read_b128 v[174:177], v162 offset:2048
	ds_read_b128 v[178:181], v162 offset:3072
	s_add_u32 s50, s56, 0x1000
	s_addc_u32 s51, s57, 0
	s_mov_b32 m0, s61
	ds_read_b128 v[182:185], v200 offset:32768
	ds_read_b128 v[186:189], v200 offset:33792
	ds_read_b128 v[190:193], v200 offset:34816
	ds_read_b128 v[194:197], v200 offset:35840
	ds_read_b128 v[202:205], v200 offset:36864
	ds_read_b128 v[206:209], v200 offset:37888
	ds_read_b128 v[210:213], v200 offset:38912
	ds_read_b128 v[214:217], v200 offset:39936
	global_load_lds_dwordx4 v154, s[50:51]
	s_mov_b32 m0, s62
	s_nop 0
	global_load_lds_dwordx4 v158, s[50:51]
	s_waitcnt vmcnt(8) lgkmcnt(0)
	s_barrier
	v_mfma_f32_16x16x32_bf16 v[118:121], v[130:133], v[182:185], v[118:121]
	v_mfma_f32_16x16x32_bf16 v[118:121], v[134:137], v[186:189], v[118:121]
	v_mfma_f32_16x16x32_bf16 v[110:113], v[134:137], v[194:197], v[110:113]
	v_mfma_f32_16x16x32_bf16 v[110:113], v[130:133], v[190:193], v[110:113]
	v_mfma_f32_16x16x32_bf16 v[94:97], v[130:133], v[202:205], v[94:97]
	v_mfma_f32_16x16x32_bf16 v[94:97], v[134:137], v[206:209], v[94:97]
	v_mfma_f32_16x16x32_bf16 v[78:81], v[134:137], v[214:217], v[78:81]
	v_mfma_f32_16x16x32_bf16 v[78:81], v[130:133], v[210:213], v[78:81]
	v_mfma_f32_16x16x32_bf16 v[74:77], v[138:141], v[210:213], v[74:77]
	v_mfma_f32_16x16x32_bf16 v[74:77], v[142:145], v[214:217], v[74:77]
	v_mfma_f32_16x16x32_bf16 v[90:93], v[142:145], v[206:209], v[90:93]
	v_mfma_f32_16x16x32_bf16 v[90:93], v[138:141], v[202:205], v[90:93]
	v_mfma_f32_16x16x32_bf16 v[106:109], v[138:141], v[190:193], v[106:109]
	v_mfma_f32_16x16x32_bf16 v[106:109], v[142:145], v[194:197], v[106:109]
	v_mfma_f32_16x16x32_bf16 v[122:125], v[142:145], v[186:189], v[122:125]
	v_mfma_f32_16x16x32_bf16 v[122:125], v[138:141], v[182:185], v[122:125]
	v_mfma_f32_16x16x32_bf16 v[126:129], v[146:149], v[182:185], v[126:129]
	v_mfma_f32_16x16x32_bf16 v[126:129], v[150:153], v[186:189], v[126:129]
	v_mfma_f32_16x16x32_bf16 v[102:105], v[150:153], v[194:197], v[102:105]
	v_mfma_f32_16x16x32_bf16 v[102:105], v[146:149], v[190:193], v[102:105]
	v_mfma_f32_16x16x32_bf16 v[86:89], v[146:149], v[202:205], v[86:89]
	v_mfma_f32_16x16x32_bf16 v[86:89], v[150:153], v[206:209], v[86:89]
	v_mfma_f32_16x16x32_bf16 v[70:73], v[150:153], v[214:217], v[70:73]
	v_mfma_f32_16x16x32_bf16 v[70:73], v[146:149], v[210:213], v[70:73]
	v_mfma_f32_16x16x32_bf16 v[66:69], v[174:177], v[210:213], v[66:69]
	v_mfma_f32_16x16x32_bf16 v[66:69], v[178:181], v[214:217], v[66:69]
	v_mfma_f32_16x16x32_bf16 v[82:85], v[178:181], v[206:209], v[82:85]
	v_mfma_f32_16x16x32_bf16 v[82:85], v[174:177], v[202:205], v[82:85]
	v_mfma_f32_16x16x32_bf16 v[98:101], v[174:177], v[190:193], v[98:101]
	v_mfma_f32_16x16x32_bf16 v[98:101], v[178:181], v[194:197], v[98:101]
	v_mfma_f32_16x16x32_bf16 v[114:117], v[178:181], v[186:189], v[114:117]
	v_mfma_f32_16x16x32_bf16 v[114:117], v[174:177], v[182:185], v[114:117]
	s_barrier
	s_add_i32 s50, s78, s41
	s_mov_b32 m0, s50
	ds_read_b128 v[182:185], v200 offset:49152
	ds_read_b128 v[186:189], v200 offset:50176
	ds_read_b128 v[190:193], v200 offset:51200
	ds_read_b128 v[194:197], v200 offset:52224
	ds_read_b128 v[202:205], v200 offset:53248
	ds_read_b128 v[206:209], v200 offset:54272
	ds_read_b128 v[210:213], v200 offset:55296
	ds_read_b128 v[214:217], v200 offset:56320
	s_add_u32 s98, s54, s14
	s_addc_u32 s99, s55, s15
	global_load_lds_dwordx4 v156, s[98:99]
	s_add_i32 m0, s50, 0x2000
	s_add_u32 s50, s54, 0x20080
	v_lshl_add_u64 v[218:219], v[220:221], 0, s[14:15]
	s_addc_u32 s51, s55, 0
	s_add_i32 s54, s79, s41
	global_load_lds_dwordx4 v[218:219], off
	s_mov_b32 m0, s54
	s_nop 0
	global_load_lds_dwordx4 v156, s[50:51]
	s_add_i32 m0, s54, 0x2000
	s_nop 0
	global_load_lds_dwordx4 v160, s[50:51]
	s_mov_b32 m0, s69
	s_nop 0
	global_load_lds_dwordx4 v154, s[52:53]
	s_mov_b32 m0, s70
	s_nop 0
	global_load_lds_dwordx4 v158, s[52:53]
	s_waitcnt vmcnt(8) lgkmcnt(0)
	s_barrier
	v_mfma_f32_16x16x32_bf16 v[62:65], v[130:133], v[182:185], v[62:65]
	v_mfma_f32_16x16x32_bf16 v[62:65], v[134:137], v[186:189], v[62:65]
	v_mfma_f32_16x16x32_bf16 v[46:49], v[134:137], v[194:197], v[46:49]
	v_mfma_f32_16x16x32_bf16 v[46:49], v[130:133], v[190:193], v[46:49]
	v_mfma_f32_16x16x32_bf16 v[30:33], v[130:133], v[202:205], v[30:33]
	v_mfma_f32_16x16x32_bf16 v[30:33], v[134:137], v[206:209], v[30:33]
	v_mfma_f32_16x16x32_bf16 v[14:17], v[134:137], v[214:217], v[14:17]
	v_mfma_f32_16x16x32_bf16 v[14:17], v[130:133], v[210:213], v[14:17]
	v_mfma_f32_16x16x32_bf16 v[10:13], v[138:141], v[210:213], v[10:13]
	v_mfma_f32_16x16x32_bf16 v[10:13], v[142:145], v[214:217], v[10:13]
	v_mfma_f32_16x16x32_bf16 v[26:29], v[142:145], v[206:209], v[26:29]
	v_mfma_f32_16x16x32_bf16 v[26:29], v[138:141], v[202:205], v[26:29]
	v_mfma_f32_16x16x32_bf16 v[42:45], v[138:141], v[190:193], v[42:45]
	v_mfma_f32_16x16x32_bf16 v[42:45], v[142:145], v[194:197], v[42:45]
	v_mfma_f32_16x16x32_bf16 v[58:61], v[142:145], v[186:189], v[58:61]
	v_mfma_f32_16x16x32_bf16 v[58:61], v[138:141], v[182:185], v[58:61]
	v_mfma_f32_16x16x32_bf16 v[54:57], v[146:149], v[182:185], v[54:57]
	v_mfma_f32_16x16x32_bf16 v[54:57], v[150:153], v[186:189], v[54:57]
	v_mfma_f32_16x16x32_bf16 v[38:41], v[150:153], v[194:197], v[38:41]
	v_mfma_f32_16x16x32_bf16 v[38:41], v[146:149], v[190:193], v[38:41]
	v_mfma_f32_16x16x32_bf16 v[22:25], v[146:149], v[202:205], v[22:25]
	v_mfma_f32_16x16x32_bf16 v[22:25], v[150:153], v[206:209], v[22:25]
	v_mfma_f32_16x16x32_bf16 v[6:9], v[150:153], v[214:217], v[6:9]
	v_mfma_f32_16x16x32_bf16 v[6:9], v[146:149], v[210:213], v[6:9]
	v_mfma_f32_16x16x32_bf16 v[2:5], v[174:177], v[210:213], v[2:5]
	v_mfma_f32_16x16x32_bf16 v[2:5], v[178:181], v[214:217], v[2:5]
	v_mfma_f32_16x16x32_bf16 v[18:21], v[178:181], v[206:209], v[18:21]
	v_mfma_f32_16x16x32_bf16 v[18:21], v[174:177], v[202:205], v[18:21]
	v_mfma_f32_16x16x32_bf16 v[34:37], v[174:177], v[190:193], v[34:37]
	v_mfma_f32_16x16x32_bf16 v[34:37], v[178:181], v[194:197], v[34:37]
	v_mfma_f32_16x16x32_bf16 v[50:53], v[178:181], v[186:189], v[50:53]
	v_mfma_f32_16x16x32_bf16 v[50:53], v[174:177], v[182:185], v[50:53]
	s_barrier
	s_add_u32 s23, s23, 0x100
	s_addc_u32 s25, s25, 0
	s_add_u32 s34, s34, 0x800000
	s_addc_u32 s35, s35, 0
	s_cmp_ge_i32 s31, s67
	s_mov_b32 s52, s31
	s_cbranch_scc0 .LBB0_599

.LBB0_740:
	v_add_u32_e32 v144, s88, v188
	v_add_u32_e32 v160, s89, v188
	ds_read_b128 v[132:135], v144
	ds_read_b128 v[136:139], v144 offset:1024
	ds_read_b128 v[140:143], v144 offset:2048
	ds_read_b128 v[144:147], v144 offset:3072
	ds_read_b128 v[148:151], v160
	ds_read_b128 v[152:155], v160 offset:1024
	ds_read_b128 v[156:159], v160 offset:2048
	ds_read_b128 v[184:187], v160 offset:3072
	s_add_i32 s92, s55, 2
	s_add_u32 s50, s60, 0x3fc000
	s_addc_u32 s51, s61, 0
	s_cmp_eq_u32 s87, s55
	s_cselect_b32 s70, s64, s50
	s_cselect_b32 s71, s65, s51
	s_cselect_b32 s69, s67, s53
	s_cselect_b32 s68, s66, s13
	s_add_u32 s62, s70, 0x400000
	s_addc_u32 s63, s71, 0
	s_add_i32 m0, s77, 0xc000
	ds_read_b128 v[192:195], v189
	ds_read_b128 v[196:199], v189 offset:1024
	ds_read_b128 v[200:203], v189 offset:2048
	ds_read_b128 v[204:207], v189 offset:3072
	ds_read_b128 v[208:211], v189 offset:4096
	ds_read_b128 v[212:215], v189 offset:5120
	ds_read_b128 v[216:219], v189 offset:6144
	ds_read_b128 v[220:223], v189 offset:7168
	global_load_lds_dwordx4 v176, s[60:61]
	s_add_i32 m0, s77, 0xe000
	s_nop 0
	global_load_lds_dwordx4 v178, s[60:61]
	s_waitcnt vmcnt(8) lgkmcnt(0)
	s_barrier
	v_mfma_f32_16x16x32_bf16 v[30:33], v[132:135], v[192:195], v[30:33]
	v_mfma_f32_16x16x32_bf16 v[30:33], v[136:139], v[196:199], v[30:33]
	v_mfma_f32_16x16x32_bf16 v[86:89], v[136:139], v[204:207], v[86:89]
	v_mfma_f32_16x16x32_bf16 v[86:89], v[132:135], v[200:203], v[86:89]
	v_mfma_f32_16x16x32_bf16 v[94:97], v[132:135], v[208:211], v[94:97]
	v_mfma_f32_16x16x32_bf16 v[94:97], v[136:139], v[212:215], v[94:97]
	v_mfma_f32_16x16x32_bf16 v[90:93], v[136:139], v[220:223], v[90:93]
	v_mfma_f32_16x16x32_bf16 v[90:93], v[132:135], v[216:219], v[90:93]
	v_mfma_f32_16x16x32_bf16 v[78:81], v[140:143], v[216:219], v[78:81]
	v_mfma_f32_16x16x32_bf16 v[78:81], v[144:147], v[220:223], v[78:81]
	v_mfma_f32_16x16x32_bf16 v[82:85], v[144:147], v[212:215], v[82:85]
	v_mfma_f32_16x16x32_bf16 v[82:85], v[140:143], v[208:211], v[82:85]
	v_mfma_f32_16x16x32_bf16 v[66:69], v[140:143], v[200:203], v[66:69]
	v_mfma_f32_16x16x32_bf16 v[66:69], v[144:147], v[204:207], v[66:69]
	v_mfma_f32_16x16x32_bf16 v[26:29], v[144:147], v[196:199], v[26:29]
	v_mfma_f32_16x16x32_bf16 v[26:29], v[140:143], v[192:195], v[26:29]
	v_mfma_f32_16x16x32_bf16 v[50:53], v[148:151], v[192:195], v[50:53]
	v_mfma_f32_16x16x32_bf16 v[50:53], v[152:155], v[196:199], v[50:53]
	v_mfma_f32_16x16x32_bf16 v[14:17], v[152:155], v[204:207], v[14:17]
	v_mfma_f32_16x16x32_bf16 v[14:17], v[148:151], v[200:203], v[14:17]
	v_mfma_f32_16x16x32_bf16 v[22:25], v[148:151], v[208:211], v[22:25]
	v_mfma_f32_16x16x32_bf16 v[22:25], v[152:155], v[212:215], v[22:25]
	v_mfma_f32_16x16x32_bf16 v[18:21], v[152:155], v[220:223], v[18:21]
	v_mfma_f32_16x16x32_bf16 v[18:21], v[148:151], v[216:219], v[18:21]
	v_mfma_f32_16x16x32_bf16 v[6:9], v[156:159], v[216:219], v[6:9]
	v_mfma_f32_16x16x32_bf16 v[6:9], v[184:187], v[220:223], v[6:9]
	v_mfma_f32_16x16x32_bf16 v[10:13], v[184:187], v[212:215], v[10:13]
	v_mfma_f32_16x16x32_bf16 v[10:13], v[156:159], v[208:211], v[10:13]
	v_mfma_f32_16x16x32_bf16 v[2:5], v[156:159], v[200:203], v[2:5]
	v_mfma_f32_16x16x32_bf16 v[2:5], v[184:187], v[204:207], v[2:5]
	v_mfma_f32_16x16x32_bf16 v[42:45], v[184:187], v[196:199], v[42:45]
	v_mfma_f32_16x16x32_bf16 v[42:45], v[156:159], v[192:195], v[42:45]
	s_barrier
	s_add_i32 s50, s88, s76
	s_mov_b32 m0, s50
	ds_read_b128 v[192:195], v189 offset:16384
	ds_read_b128 v[196:199], v189 offset:17408
	ds_read_b128 v[200:203], v189 offset:18432
	ds_read_b128 v[204:207], v189 offset:19456
	ds_read_b128 v[208:211], v189 offset:20480
	ds_read_b128 v[212:215], v189 offset:21504
	ds_read_b128 v[216:219], v189 offset:22528
	ds_read_b128 v[220:223], v189 offset:23552
	global_load_lds_dwordx4 v164, s[68:69]
	s_add_i32 m0, s50, 0x2000
	s_add_u32 s50, s68, 0x10000
	s_addc_u32 s51, s69, 0
	s_add_i32 s55, s89, s76
	global_load_lds_dwordx4 v168, s[68:69]
	s_mov_b32 m0, s55
	s_nop 0
	global_load_lds_dwordx4 v164, s[50:51]
	s_add_i32 m0, s55, 0x2000
	s_nop 0
	global_load_lds_dwordx4 v168, s[50:51]
	s_mov_b32 m0, s77
	s_nop 0
	global_load_lds_dwordx4 v162, s[70:71]
	s_mov_b32 m0, s78
	s_nop 0
	global_load_lds_dwordx4 v166, s[70:71]
	s_waitcnt vmcnt(8) lgkmcnt(0)
	s_barrier
	v_mfma_f32_16x16x32_bf16 v[118:121], v[132:135], v[192:195], v[118:121]
	v_mfma_f32_16x16x32_bf16 v[118:121], v[136:139], v[196:199], v[118:121]
	v_mfma_f32_16x16x32_bf16 v[114:117], v[136:139], v[204:207], v[114:117]
	v_mfma_f32_16x16x32_bf16 v[114:117], v[132:135], v[200:203], v[114:117]
	v_mfma_f32_16x16x32_bf16 v[126:129], v[132:135], v[208:211], v[126:129]
	v_mfma_f32_16x16x32_bf16 v[126:129], v[136:139], v[212:215], v[126:129]
	v_mfma_f32_16x16x32_bf16 v[122:125], v[136:139], v[220:223], v[122:125]
	v_mfma_f32_16x16x32_bf16 v[122:125], v[132:135], v[216:219], v[122:125]
	v_mfma_f32_16x16x32_bf16 v[106:109], v[140:143], v[216:219], v[106:109]
	v_mfma_f32_16x16x32_bf16 v[106:109], v[144:147], v[220:223], v[106:109]
	v_mfma_f32_16x16x32_bf16 v[110:113], v[144:147], v[212:215], v[110:113]
	v_mfma_f32_16x16x32_bf16 v[110:113], v[140:143], v[208:211], v[110:113]
	v_mfma_f32_16x16x32_bf16 v[98:101], v[140:143], v[200:203], v[98:101]
	v_mfma_f32_16x16x32_bf16 v[98:101], v[144:147], v[204:207], v[98:101]
	v_mfma_f32_16x16x32_bf16 v[102:105], v[144:147], v[196:199], v[102:105]
	v_mfma_f32_16x16x32_bf16 v[102:105], v[140:143], v[192:195], v[102:105]
	v_mfma_f32_16x16x32_bf16 v[62:65], v[148:151], v[192:195], v[62:65]
	v_mfma_f32_16x16x32_bf16 v[62:65], v[152:155], v[196:199], v[62:65]
	v_mfma_f32_16x16x32_bf16 v[58:61], v[152:155], v[204:207], v[58:61]
	v_mfma_f32_16x16x32_bf16 v[58:61], v[148:151], v[200:203], v[58:61]
	v_mfma_f32_16x16x32_bf16 v[74:77], v[148:151], v[208:211], v[74:77]
	v_mfma_f32_16x16x32_bf16 v[74:77], v[152:155], v[212:215], v[74:77]
	v_mfma_f32_16x16x32_bf16 v[70:73], v[152:155], v[220:223], v[70:73]
	v_mfma_f32_16x16x32_bf16 v[70:73], v[148:151], v[216:219], v[70:73]
	v_mfma_f32_16x16x32_bf16 v[46:49], v[156:159], v[216:219], v[46:49]
	v_mfma_f32_16x16x32_bf16 v[46:49], v[184:187], v[220:223], v[46:49]
	v_mfma_f32_16x16x32_bf16 v[54:57], v[184:187], v[212:215], v[54:57]
	v_mfma_f32_16x16x32_bf16 v[54:57], v[156:159], v[208:211], v[54:57]
	v_mfma_f32_16x16x32_bf16 v[34:37], v[156:159], v[200:203], v[34:37]
	v_mfma_f32_16x16x32_bf16 v[34:37], v[184:187], v[204:207], v[34:37]
	v_mfma_f32_16x16x32_bf16 v[38:41], v[184:187], v[196:199], v[38:41]
	v_mfma_f32_16x16x32_bf16 v[38:41], v[156:159], v[192:195], v[38:41]
	s_barrier
	s_add_i32 s55, 0, 0x18000
	s_add_i32 s93, 0, 0x1c000
	v_add_u32_e32 v144, s55, v188
	v_add_u32_e32 v184, s93, v188
	ds_read_b128 v[132:135], v144
	ds_read_b128 v[136:139], v144 offset:1024
	ds_read_b128 v[140:143], v144 offset:2048
	ds_read_b128 v[144:147], v144 offset:3072
	ds_read_b128 v[148:151], v184
	ds_read_b128 v[152:155], v184 offset:1024
	ds_read_b128 v[156:159], v184 offset:2048
	ds_read_b128 v[184:187], v184 offset:3072
	s_add_u32 s50, s70, 0x4000
	s_addc_u32 s51, s71, 0
	s_mov_b32 m0, s79
	ds_read_b128 v[192:195], v189 offset:32768
	ds_read_b128 v[196:199], v189 offset:33792
	ds_read_b128 v[200:203], v189 offset:34816
	ds_read_b128 v[204:207], v189 offset:35840
	ds_read_b128 v[208:211], v189 offset:36864
	ds_read_b128 v[212:215], v189 offset:37888
	ds_read_b128 v[216:219], v189 offset:38912
	ds_read_b128 v[220:223], v189 offset:39936
	global_load_lds_dwordx4 v162, s[50:51]
	s_mov_b32 m0, s80
	s_nop 0
	global_load_lds_dwordx4 v166, s[50:51]
	s_waitcnt vmcnt(8) lgkmcnt(0)
	s_barrier
	v_mfma_f32_16x16x32_bf16 v[30:33], v[132:135], v[192:195], v[30:33]
	v_mfma_f32_16x16x32_bf16 v[30:33], v[136:139], v[196:199], v[30:33]
	v_mfma_f32_16x16x32_bf16 v[86:89], v[136:139], v[204:207], v[86:89]
	v_mfma_f32_16x16x32_bf16 v[86:89], v[132:135], v[200:203], v[86:89]
	v_mfma_f32_16x16x32_bf16 v[94:97], v[132:135], v[208:211], v[94:97]
	v_mfma_f32_16x16x32_bf16 v[94:97], v[136:139], v[212:215], v[94:97]
	v_mfma_f32_16x16x32_bf16 v[90:93], v[136:139], v[220:223], v[90:93]
	v_mfma_f32_16x16x32_bf16 v[90:93], v[132:135], v[216:219], v[90:93]
	v_mfma_f32_16x16x32_bf16 v[78:81], v[140:143], v[216:219], v[78:81]
	v_mfma_f32_16x16x32_bf16 v[78:81], v[144:147], v[220:223], v[78:81]
	v_mfma_f32_16x16x32_bf16 v[82:85], v[144:147], v[212:215], v[82:85]
	v_mfma_f32_16x16x32_bf16 v[82:85], v[140:143], v[208:211], v[82:85]
	v_mfma_f32_16x16x32_bf16 v[66:69], v[140:143], v[200:203], v[66:69]
	v_mfma_f32_16x16x32_bf16 v[66:69], v[144:147], v[204:207], v[66:69]
	v_mfma_f32_16x16x32_bf16 v[26:29], v[144:147], v[196:199], v[26:29]
	v_mfma_f32_16x16x32_bf16 v[26:29], v[140:143], v[192:195], v[26:29]
	v_mfma_f32_16x16x32_bf16 v[50:53], v[148:151], v[192:195], v[50:53]
	v_mfma_f32_16x16x32_bf16 v[50:53], v[152:155], v[196:199], v[50:53]
	v_mfma_f32_16x16x32_bf16 v[14:17], v[152:155], v[204:207], v[14:17]
	v_mfma_f32_16x16x32_bf16 v[14:17], v[148:151], v[200:203], v[14:17]
	v_mfma_f32_16x16x32_bf16 v[22:25], v[148:151], v[208:211], v[22:25]
	v_mfma_f32_16x16x32_bf16 v[22:25], v[152:155], v[212:215], v[22:25]
	v_mfma_f32_16x16x32_bf16 v[18:21], v[152:155], v[220:223], v[18:21]
	v_mfma_f32_16x16x32_bf16 v[18:21], v[148:151], v[216:219], v[18:21]
	v_mfma_f32_16x16x32_bf16 v[6:9], v[156:159], v[216:219], v[6:9]
	v_mfma_f32_16x16x32_bf16 v[6:9], v[184:187], v[220:223], v[6:9]
	v_mfma_f32_16x16x32_bf16 v[10:13], v[184:187], v[212:215], v[10:13]
	v_mfma_f32_16x16x32_bf16 v[10:13], v[156:159], v[208:211], v[10:13]
	v_mfma_f32_16x16x32_bf16 v[2:5], v[156:159], v[200:203], v[2:5]
	v_mfma_f32_16x16x32_bf16 v[2:5], v[184:187], v[204:207], v[2:5]
	v_mfma_f32_16x16x32_bf16 v[42:45], v[184:187], v[196:199], v[42:45]
	v_mfma_f32_16x16x32_bf16 v[42:45], v[156:159], v[192:195], v[42:45]
	s_barrier
	s_add_i32 s50, s55, s76
	s_mov_b32 m0, s50
	ds_read_b128 v[192:195], v189 offset:49152
	ds_read_b128 v[196:199], v189 offset:50176
	ds_read_b128 v[200:203], v189 offset:51200
	ds_read_b128 v[204:207], v189 offset:52224
	ds_read_b128 v[208:211], v189 offset:53248
	ds_read_b128 v[212:215], v189 offset:54272
	ds_read_b128 v[216:219], v189 offset:55296
	ds_read_b128 v[220:223], v189 offset:56320
	s_add_u32 s98, s68, s14
	s_addc_u32 s99, s69, s15
	global_load_lds_dwordx4 v164, s[98:99]
	s_add_i32 m0, s50, 0x2000
	s_add_u32 s50, s68, 0x10080
	s_addc_u32 s51, s69, 0
	s_add_i32 s55, s93, s76
	s_add_u32 s100, s68, s14
	s_addc_u32 s101, s69, s15
	global_load_lds_dwordx4 v168, s[100:101]
	s_mov_b32 m0, s55
	s_nop 0
	global_load_lds_dwordx4 v164, s[50:51]
	s_add_i32 m0, s55, 0x2000
	s_nop 0
	global_load_lds_dwordx4 v168, s[50:51]
	s_mov_b32 m0, s84
	s_nop 0
	global_load_lds_dwordx4 v162, s[62:63]
	s_mov_b32 m0, s85
	s_nop 0
	global_load_lds_dwordx4 v166, s[62:63]
	s_waitcnt vmcnt(8) lgkmcnt(0)
	s_barrier
	v_mfma_f32_16x16x32_bf16 v[118:121], v[132:135], v[192:195], v[118:121]
	v_mfma_f32_16x16x32_bf16 v[118:121], v[136:139], v[196:199], v[118:121]
	v_mfma_f32_16x16x32_bf16 v[114:117], v[136:139], v[204:207], v[114:117]
	v_mfma_f32_16x16x32_bf16 v[114:117], v[132:135], v[200:203], v[114:117]
	v_mfma_f32_16x16x32_bf16 v[126:129], v[132:135], v[208:211], v[126:129]
	v_mfma_f32_16x16x32_bf16 v[126:129], v[136:139], v[212:215], v[126:129]
	v_mfma_f32_16x16x32_bf16 v[122:125], v[136:139], v[220:223], v[122:125]
	v_mfma_f32_16x16x32_bf16 v[122:125], v[132:135], v[216:219], v[122:125]
	v_mfma_f32_16x16x32_bf16 v[106:109], v[140:143], v[216:219], v[106:109]
	v_mfma_f32_16x16x32_bf16 v[106:109], v[144:147], v[220:223], v[106:109]
	v_mfma_f32_16x16x32_bf16 v[110:113], v[144:147], v[212:215], v[110:113]
	v_mfma_f32_16x16x32_bf16 v[110:113], v[140:143], v[208:211], v[110:113]
	v_mfma_f32_16x16x32_bf16 v[98:101], v[140:143], v[200:203], v[98:101]
	v_mfma_f32_16x16x32_bf16 v[98:101], v[144:147], v[204:207], v[98:101]
	v_mfma_f32_16x16x32_bf16 v[102:105], v[144:147], v[196:199], v[102:105]
	v_mfma_f32_16x16x32_bf16 v[102:105], v[140:143], v[192:195], v[102:105]
	v_mfma_f32_16x16x32_bf16 v[62:65], v[148:151], v[192:195], v[62:65]
	v_mfma_f32_16x16x32_bf16 v[62:65], v[152:155], v[196:199], v[62:65]
	v_mfma_f32_16x16x32_bf16 v[58:61], v[152:155], v[204:207], v[58:61]
	v_mfma_f32_16x16x32_bf16 v[58:61], v[148:151], v[200:203], v[58:61]
	v_mfma_f32_16x16x32_bf16 v[74:77], v[148:151], v[208:211], v[74:77]
	v_mfma_f32_16x16x32_bf16 v[74:77], v[152:155], v[212:215], v[74:77]
	v_mfma_f32_16x16x32_bf16 v[70:73], v[152:155], v[220:223], v[70:73]
	v_mfma_f32_16x16x32_bf16 v[70:73], v[148:151], v[216:219], v[70:73]
	v_mfma_f32_16x16x32_bf16 v[46:49], v[156:159], v[216:219], v[46:49]
	v_mfma_f32_16x16x32_bf16 v[46:49], v[184:187], v[220:223], v[46:49]
	v_mfma_f32_16x16x32_bf16 v[54:57], v[184:187], v[212:215], v[54:57]
	v_mfma_f32_16x16x32_bf16 v[54:57], v[156:159], v[208:211], v[54:57]
	v_mfma_f32_16x16x32_bf16 v[34:37], v[156:159], v[200:203], v[34:37]
	v_mfma_f32_16x16x32_bf16 v[34:37], v[184:187], v[204:207], v[34:37]
	v_mfma_f32_16x16x32_bf16 v[38:41], v[184:187], v[196:199], v[38:41]
	v_mfma_f32_16x16x32_bf16 v[38:41], v[156:159], v[192:195], v[38:41]
	s_barrier
	s_add_u32 s13, s13, 0x100
	s_addc_u32 s53, s53, 0
	s_add_u32 s60, s60, 0x800000
	s_addc_u32 s61, s61, 0
	s_cmp_ge_i32 s92, s83
	s_cbranch_scc0 .LBB0_738

.LBB0_872:
	s_add_i32 s77, s52, 2
	s_add_u32 s50, s34, 0xfffc0080
	s_addc_u32 s51, s35, -1
	s_cmp_eq_u32 s70, s52
	s_cselect_b32 s52, s30, s21
	s_cselect_b32 s55, s29, s51
	s_cselect_b32 s54, s28, s50
	s_cselect_b32 s53, s31, s23
	ds_read_b128 v[150:153], v246
	ds_read_b128 v[154:157], v246 offset:1024
	ds_read_b128 v[158:161], v246 offset:2048
	ds_read_b128 v[162:165], v246 offset:3072
	ds_read_b128 v[166:169], v247
	ds_read_b128 v[170:173], v247 offset:1024
	ds_read_b128 v[174:177], v247 offset:2048
	ds_read_b128 v[178:181], v247 offset:3072
	ds_read_b128 v[182:185], v149
	ds_read_b128 v[186:189], v149 offset:1024
	ds_read_b128 v[190:193], v149 offset:2048
	ds_read_b128 v[194:197], v149 offset:3072
	ds_read_b128 v[198:201], v149 offset:4096
	ds_read_b128 v[202:205], v149 offset:5120
	ds_read_b128 v[206:209], v149 offset:6144
	ds_read_b128 v[210:213], v149 offset:7168
	s_add_i32 m0, s60, 0xc000
	s_nop 0
	global_load_lds_dwordx4 v132, s[34:35]
	s_add_i32 m0, s60, 0xe000
	s_nop 0
	global_load_lds_dwordx4 v134, s[34:35]
	s_waitcnt vmcnt(8) lgkmcnt(0)
	s_barrier
	v_mfma_f32_16x16x32_bf16 v[78:81], v[150:153], v[182:185], v[78:81]
	v_mfma_f32_16x16x32_bf16 v[78:81], v[154:157], v[186:189], v[78:81]
	v_mfma_f32_16x16x32_bf16 v[66:69], v[154:157], v[194:197], v[66:69]
	v_mfma_f32_16x16x32_bf16 v[66:69], v[150:153], v[190:193], v[66:69]
	v_mfma_f32_16x16x32_bf16 v[70:73], v[150:153], v[198:201], v[70:73]
	v_mfma_f32_16x16x32_bf16 v[70:73], v[154:157], v[202:205], v[70:73]
	v_mfma_f32_16x16x32_bf16 v[74:77], v[154:157], v[210:213], v[74:77]
	v_mfma_f32_16x16x32_bf16 v[74:77], v[150:153], v[206:209], v[74:77]
	v_mfma_f32_16x16x32_bf16 v[10:13], v[158:161], v[206:209], v[10:13]
	v_mfma_f32_16x16x32_bf16 v[10:13], v[162:165], v[210:213], v[10:13]
	v_mfma_f32_16x16x32_bf16 v[6:9], v[162:165], v[202:205], v[6:9]
	v_mfma_f32_16x16x32_bf16 v[6:9], v[158:161], v[198:201], v[6:9]
	v_mfma_f32_16x16x32_bf16 v[2:5], v[158:161], v[190:193], v[2:5]
	v_mfma_f32_16x16x32_bf16 v[2:5], v[162:165], v[194:197], v[2:5]
	v_mfma_f32_16x16x32_bf16 v[14:17], v[162:165], v[186:189], v[14:17]
	v_mfma_f32_16x16x32_bf16 v[14:17], v[158:161], v[182:185], v[14:17]
	v_mfma_f32_16x16x32_bf16 v[98:101], v[166:169], v[182:185], v[98:101]
	v_mfma_f32_16x16x32_bf16 v[98:101], v[170:173], v[186:189], v[98:101]
	v_mfma_f32_16x16x32_bf16 v[82:85], v[170:173], v[194:197], v[82:85]
	v_mfma_f32_16x16x32_bf16 v[82:85], v[166:169], v[190:193], v[82:85]
	v_mfma_f32_16x16x32_bf16 v[86:89], v[166:169], v[198:201], v[86:89]
	v_mfma_f32_16x16x32_bf16 v[86:89], v[170:173], v[202:205], v[86:89]
	v_mfma_f32_16x16x32_bf16 v[94:97], v[170:173], v[210:213], v[94:97]
	v_mfma_f32_16x16x32_bf16 v[94:97], v[166:169], v[206:209], v[94:97]
	v_mfma_f32_16x16x32_bf16 v[30:33], v[174:177], v[206:209], v[30:33]
	v_mfma_f32_16x16x32_bf16 v[30:33], v[178:181], v[210:213], v[30:33]
	v_mfma_f32_16x16x32_bf16 v[22:25], v[178:181], v[202:205], v[22:25]
	v_mfma_f32_16x16x32_bf16 v[22:25], v[174:177], v[198:201], v[22:25]
	v_mfma_f32_16x16x32_bf16 v[18:21], v[174:177], v[190:193], v[18:21]
	v_mfma_f32_16x16x32_bf16 v[18:21], v[178:181], v[194:197], v[18:21]
	v_mfma_f32_16x16x32_bf16 v[34:37], v[178:181], v[186:189], v[34:37]
	v_mfma_f32_16x16x32_bf16 v[34:37], v[174:177], v[182:185], v[34:37]
	s_barrier
	ds_read_b128 v[182:185], v149 offset:16384
	ds_read_b128 v[186:189], v149 offset:17408
	ds_read_b128 v[190:193], v149 offset:18432
	ds_read_b128 v[194:197], v149 offset:19456
	ds_read_b128 v[198:201], v149 offset:20480
	ds_read_b128 v[202:205], v149 offset:21504
	ds_read_b128 v[206:209], v149 offset:22528
	ds_read_b128 v[210:213], v149 offset:23552
	s_add_i32 s50, s73, s15
	s_mov_b32 m0, s50
	s_nop 0
	global_load_lds_dwordx4 v228, s[52:53]
	s_add_i32 m0, s50, 0x2000
	s_add_u32 s50, s52, 0x40000
	s_addc_u32 s51, s53, 0
	s_add_i32 s78, s74, s15
	global_load_lds_dwordx4 v232, s[52:53]
	s_mov_b32 m0, s78
	s_nop 0
	global_load_lds_dwordx4 v228, s[50:51]
	s_add_i32 m0, s78, 0x2000
	s_nop 0
	global_load_lds_dwordx4 v232, s[50:51]
	s_mov_b32 m0, s60
	s_nop 0
	global_load_lds_dwordx4 v226, s[54:55]
	s_mov_b32 m0, s61
	s_nop 0
	global_load_lds_dwordx4 v230, s[54:55]
	s_waitcnt vmcnt(8) lgkmcnt(0)
	s_barrier
	v_mfma_f32_16x16x32_bf16 v[90:93], v[150:153], v[182:185], v[90:93]
	v_mfma_f32_16x16x32_bf16 v[90:93], v[154:157], v[186:189], v[90:93]
	v_mfma_f32_16x16x32_bf16 v[102:105], v[154:157], v[194:197], v[102:105]
	v_mfma_f32_16x16x32_bf16 v[102:105], v[150:153], v[190:193], v[102:105]
	v_mfma_f32_16x16x32_bf16 v[106:109], v[150:153], v[198:201], v[106:109]
	v_mfma_f32_16x16x32_bf16 v[106:109], v[154:157], v[202:205], v[106:109]
	v_mfma_f32_16x16x32_bf16 v[110:113], v[154:157], v[210:213], v[110:113]
	v_mfma_f32_16x16x32_bf16 v[110:113], v[150:153], v[206:209], v[110:113]
	v_mfma_f32_16x16x32_bf16 v[46:49], v[158:161], v[206:209], v[46:49]
	v_mfma_f32_16x16x32_bf16 v[46:49], v[162:165], v[210:213], v[46:49]
	v_mfma_f32_16x16x32_bf16 v[42:45], v[162:165], v[202:205], v[42:45]
	v_mfma_f32_16x16x32_bf16 v[42:45], v[158:161], v[198:201], v[42:45]
	v_mfma_f32_16x16x32_bf16 v[38:41], v[158:161], v[190:193], v[38:41]
	v_mfma_f32_16x16x32_bf16 v[38:41], v[162:165], v[194:197], v[38:41]
	v_mfma_f32_16x16x32_bf16 v[26:29], v[162:165], v[186:189], v[26:29]
	v_mfma_f32_16x16x32_bf16 v[26:29], v[158:161], v[182:185], v[26:29]
	v_mfma_f32_16x16x32_bf16 v[114:117], v[166:169], v[182:185], v[114:117]
	v_mfma_f32_16x16x32_bf16 v[114:117], v[170:173], v[186:189], v[114:117]
	v_mfma_f32_16x16x32_bf16 v[118:121], v[170:173], v[194:197], v[118:121]
	v_mfma_f32_16x16x32_bf16 v[118:121], v[166:169], v[190:193], v[118:121]
	v_mfma_f32_16x16x32_bf16 v[122:125], v[166:169], v[198:201], v[122:125]
	v_mfma_f32_16x16x32_bf16 v[122:125], v[170:173], v[202:205], v[122:125]
	v_mfma_f32_16x16x32_bf16 v[126:129], v[170:173], v[210:213], v[126:129]
	v_mfma_f32_16x16x32_bf16 v[126:129], v[166:169], v[206:209], v[126:129]
	v_mfma_f32_16x16x32_bf16 v[62:65], v[174:177], v[206:209], v[62:65]
	v_mfma_f32_16x16x32_bf16 v[62:65], v[178:181], v[210:213], v[62:65]
	v_mfma_f32_16x16x32_bf16 v[58:61], v[178:181], v[202:205], v[58:61]
	v_mfma_f32_16x16x32_bf16 v[58:61], v[174:177], v[198:201], v[58:61]
	v_mfma_f32_16x16x32_bf16 v[54:57], v[174:177], v[190:193], v[54:57]
	v_mfma_f32_16x16x32_bf16 v[54:57], v[178:181], v[194:197], v[54:57]
	v_mfma_f32_16x16x32_bf16 v[50:53], v[178:181], v[186:189], v[50:53]
	v_mfma_f32_16x16x32_bf16 v[50:53], v[174:177], v[182:185], v[50:53]
	s_barrier
	s_add_i32 s78, 0, 0x18000
	s_add_i32 s79, 0, 0x1c000
	ds_read_b128 v[150:153], v248
	ds_read_b128 v[154:157], v248 offset:1024
	ds_read_b128 v[158:161], v248 offset:2048
	ds_read_b128 v[162:165], v248 offset:3072
	ds_read_b128 v[166:169], v249
	ds_read_b128 v[170:173], v249 offset:1024
	ds_read_b128 v[174:177], v249 offset:2048
	ds_read_b128 v[178:181], v249 offset:3072
	ds_read_b128 v[182:185], v149 offset:32768
	ds_read_b128 v[186:189], v149 offset:33792
	ds_read_b128 v[190:193], v149 offset:34816
	ds_read_b128 v[194:197], v149 offset:35840
	ds_read_b128 v[198:201], v149 offset:36864
	ds_read_b128 v[202:205], v149 offset:37888
	ds_read_b128 v[206:209], v149 offset:38912
	ds_read_b128 v[210:213], v149 offset:39936
	s_add_u32 s50, s54, 0x40000
	s_addc_u32 s51, s55, 0
	s_mov_b32 m0, s62
	s_nop 0
	global_load_lds_dwordx4 v226, s[50:51]
	s_mov_b32 m0, s63
	s_nop 0
	global_load_lds_dwordx4 v230, s[50:51]
	s_waitcnt vmcnt(8) lgkmcnt(0)
	s_barrier
	v_mfma_f32_16x16x32_bf16 v[78:81], v[150:153], v[182:185], v[78:81]
	v_mfma_f32_16x16x32_bf16 v[78:81], v[154:157], v[186:189], v[78:81]
	v_mfma_f32_16x16x32_bf16 v[66:69], v[154:157], v[194:197], v[66:69]
	v_mfma_f32_16x16x32_bf16 v[66:69], v[150:153], v[190:193], v[66:69]
	v_mfma_f32_16x16x32_bf16 v[70:73], v[150:153], v[198:201], v[70:73]
	v_mfma_f32_16x16x32_bf16 v[70:73], v[154:157], v[202:205], v[70:73]
	v_mfma_f32_16x16x32_bf16 v[74:77], v[154:157], v[210:213], v[74:77]
	v_mfma_f32_16x16x32_bf16 v[74:77], v[150:153], v[206:209], v[74:77]
	v_mfma_f32_16x16x32_bf16 v[10:13], v[158:161], v[206:209], v[10:13]
	v_mfma_f32_16x16x32_bf16 v[10:13], v[162:165], v[210:213], v[10:13]
	v_mfma_f32_16x16x32_bf16 v[6:9], v[162:165], v[202:205], v[6:9]
	v_mfma_f32_16x16x32_bf16 v[6:9], v[158:161], v[198:201], v[6:9]
	v_mfma_f32_16x16x32_bf16 v[2:5], v[158:161], v[190:193], v[2:5]
	v_mfma_f32_16x16x32_bf16 v[2:5], v[162:165], v[194:197], v[2:5]
	v_mfma_f32_16x16x32_bf16 v[14:17], v[162:165], v[186:189], v[14:17]
	v_mfma_f32_16x16x32_bf16 v[14:17], v[158:161], v[182:185], v[14:17]
	v_mfma_f32_16x16x32_bf16 v[98:101], v[166:169], v[182:185], v[98:101]
	v_mfma_f32_16x16x32_bf16 v[98:101], v[170:173], v[186:189], v[98:101]
	v_mfma_f32_16x16x32_bf16 v[82:85], v[170:173], v[194:197], v[82:85]
	v_mfma_f32_16x16x32_bf16 v[82:85], v[166:169], v[190:193], v[82:85]
	v_mfma_f32_16x16x32_bf16 v[86:89], v[166:169], v[198:201], v[86:89]
	v_mfma_f32_16x16x32_bf16 v[86:89], v[170:173], v[202:205], v[86:89]
	v_mfma_f32_16x16x32_bf16 v[94:97], v[170:173], v[210:213], v[94:97]
	v_mfma_f32_16x16x32_bf16 v[94:97], v[166:169], v[206:209], v[94:97]
	v_mfma_f32_16x16x32_bf16 v[30:33], v[174:177], v[206:209], v[30:33]
	v_mfma_f32_16x16x32_bf16 v[30:33], v[178:181], v[210:213], v[30:33]
	v_mfma_f32_16x16x32_bf16 v[22:25], v[178:181], v[202:205], v[22:25]
	v_mfma_f32_16x16x32_bf16 v[22:25], v[174:177], v[198:201], v[22:25]
	v_mfma_f32_16x16x32_bf16 v[18:21], v[174:177], v[190:193], v[18:21]
	v_mfma_f32_16x16x32_bf16 v[18:21], v[178:181], v[194:197], v[18:21]
	v_mfma_f32_16x16x32_bf16 v[34:37], v[178:181], v[186:189], v[34:37]
	v_mfma_f32_16x16x32_bf16 v[34:37], v[174:177], v[182:185], v[34:37]
	s_barrier
	ds_read_b128 v[182:185], v149 offset:49152
	ds_read_b128 v[186:189], v149 offset:50176
	ds_read_b128 v[190:193], v149 offset:51200
	ds_read_b128 v[194:197], v149 offset:52224
	ds_read_b128 v[198:201], v149 offset:53248
	ds_read_b128 v[202:205], v149 offset:54272
	ds_read_b128 v[206:209], v149 offset:55296
	ds_read_b128 v[210:213], v149 offset:56320
	s_add_u32 s98, s52, 0x80
	s_addc_u32 s99, s53, 0
	s_add_u32 s100, s54, 0x80
	s_addc_u32 s101, s55, 0
	s_add_i32 s50, s78, s15
	s_mov_b32 m0, s50
	s_nop 0
	global_load_lds_dwordx4 v228, s[98:99]
	s_add_i32 m0, s50, 0x2000
	s_add_u32 s50, s52, 0x40080
	s_addc_u32 s51, s53, 0
	global_load_lds_dwordx4 v232, s[98:99]
	s_add_i32 s52, s79, s15
	s_mov_b32 m0, s52
	s_nop 0
	global_load_lds_dwordx4 v228, s[50:51]
	s_add_i32 m0, s52, 0x2000
	s_nop 0
	global_load_lds_dwordx4 v232, s[50:51]
	s_mov_b32 m0, s68
	s_nop 0
	global_load_lds_dwordx4 v226, s[100:101]
	s_mov_b32 m0, s69
	s_nop 0
	global_load_lds_dwordx4 v230, s[100:101]
	s_waitcnt vmcnt(8) lgkmcnt(0)
	s_barrier
	v_mfma_f32_16x16x32_bf16 v[90:93], v[150:153], v[182:185], v[90:93]
	v_mfma_f32_16x16x32_bf16 v[90:93], v[154:157], v[186:189], v[90:93]
	v_mfma_f32_16x16x32_bf16 v[102:105], v[154:157], v[194:197], v[102:105]
	v_mfma_f32_16x16x32_bf16 v[102:105], v[150:153], v[190:193], v[102:105]
	v_mfma_f32_16x16x32_bf16 v[106:109], v[150:153], v[198:201], v[106:109]
	v_mfma_f32_16x16x32_bf16 v[106:109], v[154:157], v[202:205], v[106:109]
	v_mfma_f32_16x16x32_bf16 v[110:113], v[154:157], v[210:213], v[110:113]
	v_mfma_f32_16x16x32_bf16 v[110:113], v[150:153], v[206:209], v[110:113]
	v_mfma_f32_16x16x32_bf16 v[46:49], v[158:161], v[206:209], v[46:49]
	v_mfma_f32_16x16x32_bf16 v[46:49], v[162:165], v[210:213], v[46:49]
	v_mfma_f32_16x16x32_bf16 v[42:45], v[162:165], v[202:205], v[42:45]
	v_mfma_f32_16x16x32_bf16 v[42:45], v[158:161], v[198:201], v[42:45]
	v_mfma_f32_16x16x32_bf16 v[38:41], v[158:161], v[190:193], v[38:41]
	v_mfma_f32_16x16x32_bf16 v[38:41], v[162:165], v[194:197], v[38:41]
	v_mfma_f32_16x16x32_bf16 v[26:29], v[162:165], v[186:189], v[26:29]
	v_mfma_f32_16x16x32_bf16 v[26:29], v[158:161], v[182:185], v[26:29]
	v_mfma_f32_16x16x32_bf16 v[114:117], v[166:169], v[182:185], v[114:117]
	v_mfma_f32_16x16x32_bf16 v[114:117], v[170:173], v[186:189], v[114:117]
	v_mfma_f32_16x16x32_bf16 v[118:121], v[170:173], v[194:197], v[118:121]
	v_mfma_f32_16x16x32_bf16 v[118:121], v[166:169], v[190:193], v[118:121]
	v_mfma_f32_16x16x32_bf16 v[122:125], v[166:169], v[198:201], v[122:125]
	v_mfma_f32_16x16x32_bf16 v[122:125], v[170:173], v[202:205], v[122:125]
	v_mfma_f32_16x16x32_bf16 v[126:129], v[170:173], v[210:213], v[126:129]
	v_mfma_f32_16x16x32_bf16 v[126:129], v[166:169], v[206:209], v[126:129]
	v_mfma_f32_16x16x32_bf16 v[62:65], v[174:177], v[206:209], v[62:65]
	v_mfma_f32_16x16x32_bf16 v[62:65], v[178:181], v[210:213], v[62:65]
	v_mfma_f32_16x16x32_bf16 v[58:61], v[178:181], v[202:205], v[58:61]
	v_mfma_f32_16x16x32_bf16 v[58:61], v[174:177], v[198:201], v[58:61]
	v_mfma_f32_16x16x32_bf16 v[54:57], v[174:177], v[190:193], v[54:57]
	v_mfma_f32_16x16x32_bf16 v[54:57], v[178:181], v[194:197], v[54:57]
	v_mfma_f32_16x16x32_bf16 v[50:53], v[178:181], v[186:189], v[50:53]
	v_mfma_f32_16x16x32_bf16 v[50:53], v[174:177], v[182:185], v[50:53]
	s_barrier
	s_add_u32 s34, s34, 0x100
	s_addc_u32 s35, s35, 0
	s_add_u32 s21, s21, 0x100
	s_addc_u32 s23, s23, 0
	s_cmp_ge_i32 s77, s66
	s_mov_b32 s52, s77
	s_cbranch_scc0 .LBB0_872

.LBB0_1009:
	v_add_u32_e32 v0, s64, v187
	ds_read_b128 v[130:133], v0
	ds_read_b128 v[134:137], v0 offset:1024
	ds_read_b128 v[138:141], v0 offset:2048
	ds_read_b128 v[142:145], v0 offset:3072
	v_add_u32_e32 v0, s65, v187
	ds_read_b128 v[146:149], v0
	ds_read_b128 v[150:153], v0 offset:1024
	ds_read_b128 v[178:181], v0 offset:2048
	ds_read_b128 v[182:185], v0 offset:3072
	s_add_i32 s35, s42, 2
	s_add_u32 s43, s36, 0x3fc000
	s_addc_u32 s44, s37, 0
	s_cmp_eq_u32 s61, s42
	s_cselect_b32 s46, s28, s43
	s_cselect_b32 s47, s29, s44
	s_cselect_b32 s44, s30, s11
	s_cselect_b32 s45, s31, s27
	s_add_u32 s42, s46, 0x400000
	s_addc_u32 s43, s47, 0
	s_add_i32 m0, s51, 0xc000
	ds_read_b128 v[220:223], v215
	ds_read_b128 v[224:227], v215 offset:1024
	ds_read_b128 v[228:231], v215 offset:2048
	ds_read_b128 v[232:235], v215 offset:3072
	ds_read_b128 v[236:239], v215 offset:4096
	ds_read_b128 v[240:243], v215 offset:5120
	ds_read_b128 v[244:247], v215 offset:6144
	ds_read_b128 v[248:251], v215 offset:7168
	global_load_lds_dwordx4 v168, s[36:37]
	s_add_i32 m0, s51, 0xe000
	s_nop 0
	global_load_lds_dwordx4 v170, s[36:37]
	s_waitcnt vmcnt(8) lgkmcnt(0)
	s_barrier
	v_mfma_f32_16x16x32_bf16 v[114:117], v[130:133], v[220:223], v[114:117]
	v_mfma_f32_16x16x32_bf16 v[114:117], v[134:137], v[224:227], v[114:117]
	v_mfma_f32_16x16x32_bf16 v[110:113], v[134:137], v[232:235], v[110:113]
	v_mfma_f32_16x16x32_bf16 v[110:113], v[130:133], v[228:231], v[110:113]
	v_mfma_f32_16x16x32_bf16 v[94:97], v[130:133], v[236:239], v[94:97]
	v_mfma_f32_16x16x32_bf16 v[94:97], v[134:137], v[240:243], v[94:97]
	v_mfma_f32_16x16x32_bf16 v[78:81], v[134:137], v[248:251], v[78:81]
	v_mfma_f32_16x16x32_bf16 v[78:81], v[130:133], v[244:247], v[78:81]
	v_mfma_f32_16x16x32_bf16 v[70:73], v[138:141], v[244:247], v[70:73]
	v_mfma_f32_16x16x32_bf16 v[70:73], v[142:145], v[248:251], v[70:73]
	v_mfma_f32_16x16x32_bf16 v[86:89], v[142:145], v[240:243], v[86:89]
	v_mfma_f32_16x16x32_bf16 v[86:89], v[138:141], v[236:239], v[86:89]
	v_mfma_f32_16x16x32_bf16 v[102:105], v[138:141], v[228:231], v[102:105]
	v_mfma_f32_16x16x32_bf16 v[102:105], v[142:145], v[232:235], v[102:105]
	v_mfma_f32_16x16x32_bf16 v[118:121], v[142:145], v[224:227], v[118:121]
	v_mfma_f32_16x16x32_bf16 v[118:121], v[138:141], v[220:223], v[118:121]
	v_mfma_f32_16x16x32_bf16 v[126:129], v[146:149], v[220:223], v[126:129]
	v_mfma_f32_16x16x32_bf16 v[126:129], v[150:153], v[224:227], v[126:129]
	v_mfma_f32_16x16x32_bf16 v[106:109], v[150:153], v[232:235], v[106:109]
	v_mfma_f32_16x16x32_bf16 v[106:109], v[146:149], v[228:231], v[106:109]
	v_mfma_f32_16x16x32_bf16 v[90:93], v[146:149], v[236:239], v[90:93]
	v_mfma_f32_16x16x32_bf16 v[90:93], v[150:153], v[240:243], v[90:93]
	v_mfma_f32_16x16x32_bf16 v[74:77], v[150:153], v[248:251], v[74:77]
	v_mfma_f32_16x16x32_bf16 v[74:77], v[146:149], v[244:247], v[74:77]
	v_mfma_f32_16x16x32_bf16 v[66:69], v[178:181], v[244:247], v[66:69]
	v_mfma_f32_16x16x32_bf16 v[66:69], v[182:185], v[248:251], v[66:69]
	v_mfma_f32_16x16x32_bf16 v[82:85], v[182:185], v[240:243], v[82:85]
	v_mfma_f32_16x16x32_bf16 v[82:85], v[178:181], v[236:239], v[82:85]
	v_mfma_f32_16x16x32_bf16 v[98:101], v[178:181], v[228:231], v[98:101]
	v_mfma_f32_16x16x32_bf16 v[98:101], v[182:185], v[232:235], v[98:101]
	v_mfma_f32_16x16x32_bf16 v[122:125], v[182:185], v[224:227], v[122:125]
	v_mfma_f32_16x16x32_bf16 v[122:125], v[178:181], v[220:223], v[122:125]
	s_barrier
	s_add_i32 s69, s64, s49
	s_mov_b32 m0, s69
	ds_read_b128 v[220:223], v215 offset:16384
	ds_read_b128 v[224:227], v215 offset:17408
	ds_read_b128 v[228:231], v215 offset:18432
	ds_read_b128 v[232:235], v215 offset:19456
	ds_read_b128 v[236:239], v215 offset:20480
	ds_read_b128 v[240:243], v215 offset:21504
	ds_read_b128 v[244:247], v215 offset:22528
	ds_read_b128 v[248:251], v215 offset:23552
	global_load_lds_dwordx4 v156, s[44:45]
	s_add_i32 m0, s69, 0x2000
	s_add_u32 s70, s44, 0xb0000
	v_lshl_add_u64 v[172:173], s[44:45], 0, v[160:161]
	s_addc_u32 s71, s45, 0
	s_add_i32 s69, s65, s49
	global_load_lds_dwordx4 v160, s[44:45]
	s_mov_b32 m0, s69
	s_nop 0
	global_load_lds_dwordx4 v156, s[70:71]
	s_add_i32 m0, s69, 0x2000
	s_nop 0
	global_load_lds_dwordx4 v160, s[70:71]
	s_mov_b32 m0, s51
	s_nop 0
	global_load_lds_dwordx4 v154, s[46:47]
	s_mov_b32 m0, s52
	s_nop 0
	global_load_lds_dwordx4 v158, s[46:47]
	s_waitcnt vmcnt(8) lgkmcnt(0)
	s_barrier
	v_mfma_f32_16x16x32_bf16 v[50:53], v[130:133], v[220:223], v[50:53]
	v_mfma_f32_16x16x32_bf16 v[50:53], v[134:137], v[224:227], v[50:53]
	v_mfma_f32_16x16x32_bf16 v[54:57], v[142:145], v[224:227], v[54:57]
	v_mfma_f32_16x16x32_bf16 v[54:57], v[138:141], v[220:223], v[54:57]
	v_mfma_f32_16x16x32_bf16 v[46:49], v[130:133], v[228:231], v[46:49]
	v_mfma_f32_16x16x32_bf16 v[46:49], v[134:137], v[232:235], v[46:49]
	v_mfma_f32_16x16x32_bf16 v[38:41], v[142:145], v[232:235], v[38:41]
	v_mfma_f32_16x16x32_bf16 v[38:41], v[138:141], v[228:231], v[38:41]
	v_mfma_f32_16x16x32_bf16 v[30:33], v[130:133], v[236:239], v[30:33]
	v_mfma_f32_16x16x32_bf16 v[30:33], v[134:137], v[240:243], v[30:33]
	v_mfma_f32_16x16x32_bf16 v[22:25], v[142:145], v[240:243], v[22:25]
	v_mfma_f32_16x16x32_bf16 v[22:25], v[138:141], v[236:239], v[22:25]
	v_mfma_f32_16x16x32_bf16 v[14:17], v[130:133], v[244:247], v[14:17]
	v_mfma_f32_16x16x32_bf16 v[14:17], v[134:137], v[248:251], v[14:17]
	v_mfma_f32_16x16x32_bf16 v[62:65], v[150:153], v[224:227], v[62:65]
	v_mfma_f32_16x16x32_bf16 v[62:65], v[146:149], v[220:223], v[62:65]
	v_mfma_f32_16x16x32_bf16 v[58:61], v[178:181], v[220:223], v[58:61]
	v_mfma_f32_16x16x32_bf16 v[58:61], v[182:185], v[224:227], v[58:61]
	v_mfma_f32_16x16x32_bf16 v[42:45], v[150:153], v[232:235], v[42:45]
	v_mfma_f32_16x16x32_bf16 v[42:45], v[146:149], v[228:231], v[42:45]
	v_mfma_f32_16x16x32_bf16 v[34:37], v[178:181], v[228:231], v[34:37]
	v_mfma_f32_16x16x32_bf16 v[34:37], v[182:185], v[232:235], v[34:37]
	v_mfma_f32_16x16x32_bf16 v[26:29], v[150:153], v[240:243], v[26:29]
	v_mfma_f32_16x16x32_bf16 v[26:29], v[146:149], v[236:239], v[26:29]
	v_mfma_f32_16x16x32_bf16 v[18:21], v[178:181], v[236:239], v[18:21]
	v_mfma_f32_16x16x32_bf16 v[18:21], v[182:185], v[240:243], v[18:21]
	v_mfma_f32_16x16x32_bf16 v[10:13], v[150:153], v[248:251], v[10:13]
	v_mfma_f32_16x16x32_bf16 v[10:13], v[146:149], v[244:247], v[10:13]
	v_mfma_f32_16x16x32_bf16 v[6:9], v[138:141], v[244:247], v[6:9]
	v_mfma_f32_16x16x32_bf16 v[6:9], v[142:145], v[248:251], v[6:9]
	v_mfma_f32_16x16x32_bf16 v[0:3], v[178:181], v[244:247], v[2:5]
	v_mfma_f32_16x16x32_bf16 v[0:3], v[182:185], v[248:251], v[0:3]
	s_barrier
	s_add_i32 s69, 0, 0x18000
	v_add_u32_e32 v4, s69, v187
	s_add_i32 s70, 0, 0x1c000
	ds_read_b128 v[130:133], v4
	ds_read_b128 v[134:137], v4 offset:1024
	ds_read_b128 v[138:141], v4 offset:2048
	ds_read_b128 v[142:145], v4 offset:3072
	v_add_u32_e32 v4, s70, v187
	ds_read_b128 v[146:149], v4
	ds_read_b128 v[150:153], v4 offset:1024
	ds_read_b128 v[178:181], v4 offset:2048
	ds_read_b128 v[182:185], v4 offset:3072
	s_add_u32 s46, s46, 0x4000
	s_addc_u32 s47, s47, 0
	s_mov_b32 m0, s53
	ds_read_b128 v[220:223], v215 offset:32768
	ds_read_b128 v[224:227], v215 offset:33792
	ds_read_b128 v[228:231], v215 offset:34816
	ds_read_b128 v[232:235], v215 offset:35840
	ds_read_b128 v[236:239], v215 offset:36864
	ds_read_b128 v[240:243], v215 offset:37888
	ds_read_b128 v[244:247], v215 offset:38912
	ds_read_b128 v[248:251], v215 offset:39936
	global_load_lds_dwordx4 v154, s[46:47]
	s_mov_b32 m0, s54
	s_nop 0
	global_load_lds_dwordx4 v158, s[46:47]
	s_waitcnt vmcnt(8) lgkmcnt(0)
	s_barrier
	v_mfma_f32_16x16x32_bf16 v[114:117], v[130:133], v[220:223], v[114:117]
	v_mfma_f32_16x16x32_bf16 v[114:117], v[134:137], v[224:227], v[114:117]
	v_mfma_f32_16x16x32_bf16 v[110:113], v[134:137], v[232:235], v[110:113]
	v_mfma_f32_16x16x32_bf16 v[110:113], v[130:133], v[228:231], v[110:113]
	v_mfma_f32_16x16x32_bf16 v[94:97], v[130:133], v[236:239], v[94:97]
	v_mfma_f32_16x16x32_bf16 v[94:97], v[134:137], v[240:243], v[94:97]
	v_mfma_f32_16x16x32_bf16 v[78:81], v[134:137], v[248:251], v[78:81]
	v_mfma_f32_16x16x32_bf16 v[78:81], v[130:133], v[244:247], v[78:81]
	v_mfma_f32_16x16x32_bf16 v[70:73], v[138:141], v[244:247], v[70:73]
	v_mfma_f32_16x16x32_bf16 v[70:73], v[142:145], v[248:251], v[70:73]
	v_mfma_f32_16x16x32_bf16 v[86:89], v[142:145], v[240:243], v[86:89]
	v_mfma_f32_16x16x32_bf16 v[86:89], v[138:141], v[236:239], v[86:89]
	v_mfma_f32_16x16x32_bf16 v[102:105], v[138:141], v[228:231], v[102:105]
	v_mfma_f32_16x16x32_bf16 v[102:105], v[142:145], v[232:235], v[102:105]
	v_mfma_f32_16x16x32_bf16 v[118:121], v[142:145], v[224:227], v[118:121]
	v_mfma_f32_16x16x32_bf16 v[118:121], v[138:141], v[220:223], v[118:121]
	v_mfma_f32_16x16x32_bf16 v[126:129], v[146:149], v[220:223], v[126:129]
	v_mfma_f32_16x16x32_bf16 v[126:129], v[150:153], v[224:227], v[126:129]
	v_mfma_f32_16x16x32_bf16 v[106:109], v[150:153], v[232:235], v[106:109]
	v_mfma_f32_16x16x32_bf16 v[106:109], v[146:149], v[228:231], v[106:109]
	v_mfma_f32_16x16x32_bf16 v[90:93], v[146:149], v[236:239], v[90:93]
	v_mfma_f32_16x16x32_bf16 v[90:93], v[150:153], v[240:243], v[90:93]
	v_mfma_f32_16x16x32_bf16 v[74:77], v[150:153], v[248:251], v[74:77]
	v_mfma_f32_16x16x32_bf16 v[74:77], v[146:149], v[244:247], v[74:77]
	v_mfma_f32_16x16x32_bf16 v[66:69], v[178:181], v[244:247], v[66:69]
	v_mfma_f32_16x16x32_bf16 v[66:69], v[182:185], v[248:251], v[66:69]
	v_mfma_f32_16x16x32_bf16 v[82:85], v[182:185], v[240:243], v[82:85]
	v_mfma_f32_16x16x32_bf16 v[82:85], v[178:181], v[236:239], v[82:85]
	v_mfma_f32_16x16x32_bf16 v[98:101], v[178:181], v[228:231], v[98:101]
	v_mfma_f32_16x16x32_bf16 v[98:101], v[182:185], v[232:235], v[98:101]
	v_mfma_f32_16x16x32_bf16 v[122:125], v[182:185], v[224:227], v[122:125]
	v_mfma_f32_16x16x32_bf16 v[122:125], v[178:181], v[220:223], v[122:125]
	s_barrier
	s_add_i32 s46, s69, s49
	s_mov_b32 m0, s46
	ds_read_b128 v[220:223], v215 offset:49152
	ds_read_b128 v[224:227], v215 offset:50176
	ds_read_b128 v[228:231], v215 offset:51200
	ds_read_b128 v[232:235], v215 offset:52224
	ds_read_b128 v[236:239], v215 offset:53248
	ds_read_b128 v[240:243], v215 offset:54272
	ds_read_b128 v[244:247], v215 offset:55296
	ds_read_b128 v[248:251], v215 offset:56320
	s_add_u32 s98, s44, s18
	s_addc_u32 s99, s45, s19
	global_load_lds_dwordx4 v156, s[98:99]
	s_add_i32 m0, s46, 0x2000
	s_add_u32 s44, s44, 0xb0080
	v_lshl_add_u64 v[4:5], v[172:173], 0, s[18:19]
	s_addc_u32 s45, s45, 0
	s_add_i32 s46, s70, s49
	global_load_lds_dwordx4 v[4:5], off
	s_mov_b32 m0, s46
	s_nop 0
	global_load_lds_dwordx4 v156, s[44:45]
	s_add_i32 m0, s46, 0x2000
	s_nop 0
	global_load_lds_dwordx4 v160, s[44:45]
	s_mov_b32 m0, s59
	s_nop 0
	global_load_lds_dwordx4 v154, s[42:43]
	s_mov_b32 m0, s60
	s_nop 0
	global_load_lds_dwordx4 v158, s[42:43]
	s_waitcnt vmcnt(8) lgkmcnt(0)
	s_barrier
	v_mfma_f32_16x16x32_bf16 v[50:53], v[130:133], v[220:223], v[50:53]
	v_mfma_f32_16x16x32_bf16 v[50:53], v[134:137], v[224:227], v[50:53]
	v_mfma_f32_16x16x32_bf16 v[54:57], v[142:145], v[224:227], v[54:57]
	v_mfma_f32_16x16x32_bf16 v[54:57], v[138:141], v[220:223], v[54:57]
	v_mfma_f32_16x16x32_bf16 v[46:49], v[130:133], v[228:231], v[46:49]
	v_mfma_f32_16x16x32_bf16 v[46:49], v[134:137], v[232:235], v[46:49]
	v_mfma_f32_16x16x32_bf16 v[38:41], v[142:145], v[232:235], v[38:41]
	v_mfma_f32_16x16x32_bf16 v[38:41], v[138:141], v[228:231], v[38:41]
	v_mfma_f32_16x16x32_bf16 v[30:33], v[130:133], v[236:239], v[30:33]
	v_mfma_f32_16x16x32_bf16 v[30:33], v[134:137], v[240:243], v[30:33]
	v_mfma_f32_16x16x32_bf16 v[22:25], v[142:145], v[240:243], v[22:25]
	v_mfma_f32_16x16x32_bf16 v[22:25], v[138:141], v[236:239], v[22:25]
	v_mfma_f32_16x16x32_bf16 v[14:17], v[130:133], v[244:247], v[14:17]
	v_mfma_f32_16x16x32_bf16 v[14:17], v[134:137], v[248:251], v[14:17]
	v_mfma_f32_16x16x32_bf16 v[62:65], v[150:153], v[224:227], v[62:65]
	v_mfma_f32_16x16x32_bf16 v[62:65], v[146:149], v[220:223], v[62:65]
	v_mfma_f32_16x16x32_bf16 v[58:61], v[178:181], v[220:223], v[58:61]
	v_mfma_f32_16x16x32_bf16 v[58:61], v[182:185], v[224:227], v[58:61]
	v_mfma_f32_16x16x32_bf16 v[42:45], v[150:153], v[232:235], v[42:45]
	v_mfma_f32_16x16x32_bf16 v[42:45], v[146:149], v[228:231], v[42:45]
	v_mfma_f32_16x16x32_bf16 v[34:37], v[178:181], v[228:231], v[34:37]
	v_mfma_f32_16x16x32_bf16 v[34:37], v[182:185], v[232:235], v[34:37]
	v_mfma_f32_16x16x32_bf16 v[26:29], v[150:153], v[240:243], v[26:29]
	v_mfma_f32_16x16x32_bf16 v[26:29], v[146:149], v[236:239], v[26:29]
	v_mfma_f32_16x16x32_bf16 v[18:21], v[178:181], v[236:239], v[18:21]
	v_mfma_f32_16x16x32_bf16 v[18:21], v[182:185], v[240:243], v[18:21]
	v_mfma_f32_16x16x32_bf16 v[10:13], v[150:153], v[248:251], v[10:13]
	v_mfma_f32_16x16x32_bf16 v[10:13], v[146:149], v[244:247], v[10:13]
	v_mfma_f32_16x16x32_bf16 v[4:7], v[138:141], v[244:247], v[6:9]
	v_mfma_f32_16x16x32_bf16 v[6:9], v[142:145], v[248:251], v[4:7]
	v_mfma_f32_16x16x32_bf16 v[0:3], v[178:181], v[244:247], v[0:3]
	v_mfma_f32_16x16x32_bf16 v[2:5], v[182:185], v[248:251], v[0:3]
	s_barrier
	s_add_u32 s11, s11, 0x100
	s_addc_u32 s27, s27, 0
	s_add_u32 s36, s36, 0x800000
	s_addc_u32 s37, s37, 0
	s_cmp_ge_i32 s35, s58
	s_mov_b32 s42, s35
	s_cbranch_scc0 .LBB0_1009
	v_mov_b64_e32 v[234:235], v[174:175]
	s_and_b64 vcc, exec, s[22:23]
	s_cbranch_vccnz .LBB0_980
	s_branch .LBB0_981
